# GEMM main loops (gateup/down/inproj) switched to v_mfma_f32_16x16x32_bf16, accumulators permuted back to the 32x32 layout with permlane16/32 swaps at tile exit; attention epilogue gain loads hoisted
# speedup vs baseline: 1.2086x; 1.0082x over previous
; DI int tid512() { int t = threadIdx.x; asm volatile("" : "+v"(t)); return t; }
; DI unsigned voff256(size_t ld) { const int t = tid512(); return (unsigned)(((size_t)(t >> 3) * ld + (t & 7) * 8) * 2); }
; DI void gemm256(const char* a_u, unsigned a_voff, size_t astep, const char* b_u, unsigned b_voff, size_t bstep, int nk, char* smem, f32x16 (&acc)[4][2]) {
;   asm volatile("" : "+s"(nk));
;   const int t = tid512(), lane = t & 63, w = t >> 6, wm = w >> 2, wn = w & 3, r = lane & 31, h = lane >> 5;
;   const int soff = (t >> 3) * LROW + (t & 7) * 16;
;   const int aoff = (128 * wm + r) * LROW + h * 16, boff = T2 + (64 * wn + r) * LROW + h * 16;
;   u32x4 ra[4], rb[4];
; #pragma unroll
;   for (int i = 0; i < 4; ++i) { ra[i] = *(const u32x4*)(a_u + i * astep + a_voff); rb[i] = *(const u32x4*)(b_u + i * bstep + b_voff); }
;   __syncthreads();
; #pragma unroll
;   for (int i = 0; i < 4; ++i) { *(u32x4*)(smem + soff + i * 64 * LROW) = ra[i]; *(u32x4*)(smem + T2 + soff + i * 64 * LROW) = rb[i]; }
;   const int last = nk - 1;
;   {
;     const int k1 = last < 1 ? last : 1;
; #pragma unroll
;     for (int i = 0; i < 4; ++i) { ra[i] = *(const u32x4*)(a_u + i * astep + k1 * 128 + a_voff); rb[i] = *(const u32x4*)(b_u + i * bstep + k1 * 128 + b_voff); }
;   }
;   __syncthreads();
; DI void inproj_phase(const Params& p, int layer, char* smem) {
;   const bf16_t* H = (const bf16_t*)(p.ws + O_H);
;   const bf16_t* W = (const bf16_t*)(p.ws + O_WIN) + (size_t)layer * DIN * DM;
;   for (int i = 0;; ++i) {
;     const int L = tile_of(i, 32 * 24);
;     if (L < 0) break;
;     int tm, tn; tile_mn(L, 32, 24, tm, tn);
;     f32x16 acc[4][2]; zero_acc256(acc);
;     gemm256((const char*)(W + (size_t)(tn * 256) * DM), voff256(DM), (size_t)128 * DM, (const char*)(H + (size_t)(256 + tm * 256) * DM), voff256(DM), (size_t)128 * DM, DM / 64, smem, acc);
.LBB0_188:
	s_mul_hi_u32 s6, s8, 0xaaaaaaab
	s_lshr_b32 s6, s6, 6
	s_lshl_b32 s9, s6, 2
	s_sub_i32 s7, 32, s9
	s_min_i32 s10, s7, 4
	s_abs_i32 s7, s10
	v_cvt_f32_u32_e32 v2, s7
	s_sub_i32 s12, 0, s7
	s_mulk_i32 s6, 0xffa0
	s_add_i32 s6, s6, s8
	v_rcp_iflag_f32_e32 v2, v2
	s_abs_i32 s8, s6
	s_xor_b32 s11, s6, s10
	s_ashr_i32 s11, s11, 31
	v_mul_f32_e32 v2, 0x4f7ffffe, v2
	v_cvt_u32_f32_e32 v2, v2
	s_movk_i32 s16, 0xf000
	v_mov_b32_e32 v37, v181
	v_readfirstlane_b32 s13, v2
	s_mul_i32 s12, s12, s13
	s_mul_hi_u32 s12, s13, s12
	s_add_i32 s13, s13, s12
	s_mul_hi_u32 s12, s8, s13
	s_mul_i32 s13, s12, s7
	s_sub_i32 s8, s8, s13
	s_add_i32 s14, s12, 1
	s_sub_i32 s13, s8, s7
	s_cmp_ge_u32 s8, s7
	s_cselect_b32 s12, s14, s12
	s_cselect_b32 s8, s13, s8
	s_add_i32 s13, s12, 1
	s_cmp_ge_u32 s8, s7
	s_cselect_b32 s7, s13, s12
	s_xor_b32 s7, s7, s11
	s_sub_i32 s7, s7, s11
	s_mul_i32 s10, s7, s10
	s_lshl_b32 s8, s7, 8
	s_sub_i32 s6, s6, s10
	s_add_i32 s6, s6, s9
	s_ashr_i32 s9, s8, 31
	s_lshl_b64 s[8:9], s[8:9], 12
	s_add_u32 s12, s0, s8
	v_mov_b32_e32 v2, v0
	s_addc_u32 s13, s1, s9
	s_lshl_b32 s6, s6, 8
	v_lshlrev_b32_e32 v3, 4, v2
	v_and_b32_e32 v3, 0x70, v3
	v_lshlrev_b32_e32 v2, 9, v2
	s_add_i32 s8, s6, 0x100
	v_and_or_b32 v180, v2, s16, v3
	s_ashr_i32 s9, s8, 31
	v_mov_b32_e32 v2, v0
	s_lshl_b64 s[10:11], s[8:9], 12
	s_add_u32 s14, s92, s10
	v_lshlrev_b32_e32 v3, 4, v2
	v_and_b32_e32 v3, 0x70, v3
	v_lshlrev_b32_e32 v2, 9, v2
	v_lshl_add_u64 v[162:163], s[12:13], 0, v[180:181]
	s_addc_u32 s15, s93, s11
	v_and_or_b32 v36, v2, s16, v3
	v_add_co_u32_e32 v12, vcc, s84, v162
	v_lshl_add_u64 v[164:165], s[14:15], 0, v[36:37]
	s_nop 0
	v_addc_co_u32_e32 v13, vcc, 0, v163, vcc
	v_add_co_u32_e32 v16, vcc, s84, v164
	s_mov_b32 s9, 32
	s_nop 0
	v_addc_co_u32_e32 v17, vcc, 0, v165, vcc
	v_add_co_u32_e32 v20, vcc, s31, v162
	s_add_i32 s10, s9, -1
	s_nop 0
	v_addc_co_u32_e32 v21, vcc, 0, v163, vcc
	s_min_i32 s11, s10, 1
	v_add_co_u32_e32 v24, vcc, s31, v164
	s_lshl_b32 s11, s11, 7
	v_mov_b32_e32 v2, v0
	v_addc_co_u32_e32 v25, vcc, 0, v165, vcc
	s_ashr_i32 s16, s11, 31
	v_lshrrev_b32_e32 v132, 6, v0
	s_nop 0
	v_readfirstlane_b32 s61, v132
	v_and_b32_e32 v132, 63, v0
	v_and_b32_e32 v133, 15, v132
	v_lshrrev_b32_e32 v136, 4, v132
	v_bfe_u32 v137, v133, 1, 3
	v_lshlrev_b32_e32 v133, 7, v133
	s_lshr_b32 s60, s61, 2
	s_lshl_b32 s60, s60, 14
	s_add_i32 s60, s60, 16
	s_and_b32 s62, s61, 3
	s_lshl_b32 s62, s62, 13
	s_add_i32 s62, s62, 0x10010
	v_add_u32_e32 v194, 0, v136
	v_xor_b32_e32 v194, v194, v137
	v_lshl_add_u32 v194, v194, 4, v133
	v_add_u32_e32 v160, s62, v194
	v_add_u32_e32 v194, s60, v194
	v_add_u32_e32 v195, 4, v136
	v_xor_b32_e32 v195, v195, v137
	v_lshl_add_u32 v195, v195, 4, v133
	v_add_u32_e32 v161, s62, v195
	v_add_u32_e32 v195, s60, v195
	v_lshrrev_b32_e32 v133, 3, v132
	s_mov_b32 s60, 0x1000
	v_mul_lo_u32 v133, v133, s60
	v_and_b32_e32 v136, 7, v132
	v_lshrrev_b32_e32 v137, 4, v132
	v_xor_b32_e32 v164, v137, v136
	v_lshl_add_u32 v164, v164, 4, v133
	v_add_u32_e32 v165, 4, v137
	v_xor_b32_e32 v165, v165, v136
	v_lshl_add_u32 v165, v165, 4, v133
	v_add_u32_e32 v165, 0x8000, v165
	v_xor_b32_e32 v130, v137, v136
	v_lshl_add_u32 v130, v130, 4, v133
	v_add_u32_e32 v130, 0x10000, v130
	v_add_u32_e32 v131, 4, v137
	v_xor_b32_e32 v131, v131, v136
	v_lshl_add_u32 v131, v131, 4, v133
	v_add_u32_e32 v131, 0x18000, v131
	s_mul_i32 s60, s61, 0x20000
	s_add_u32 s52, s12, s60
	s_addc_u32 s53, s13, 0
	s_add_u32 s54, s14, s60
	s_addc_u32 s55, s15, 0
	s_lshl_b32 s58, s61, 12
	s_add_i32 s58, s58, 16
	s_add_i32 s59, s58, 0x10000
	s_mov_b32 s56, 0
	s_mov_b32 s57, 31
	s_add_u32 s64, s52, 0x800000
	s_addc_u32 s65, s53, 0
	s_add_u32 s66, s54, 0x0
	s_addc_u32 s67, s55, 0
	s_and_b64 s[62:63], exec, s[40:41]
	s_cselect_b32 s62, 0, 1
	s_add_i32 s60, s22, 1
	s_mul_i32 s60, s60, s88
	s_add_i32 s60, s60, s33
	s_cmp_lt_u32 s60, 96
	s_cselect_b32 s63, s57, -1
	s_cmp_eq_u32 s62, 1
	s_cselect_b32 s63, -1, s63
	s_cbranch_scc1 .Lg_inproj_first
	s_cmp_eq_u32 s22, 0
	s_cbranch_scc1 .Lg_inproj_first
	s_cmp_lt_u32 s56, s57
	s_cselect_b32 s60, 0x80, 0
	s_add_u32 s52, s52, s60
	s_addc_u32 s53, s53, 0
	s_add_u32 s54, s54, s60
	s_addc_u32 s55, s55, 0
	s_cmp_eq_u32 s56, s63
	s_cselect_b32 s52, s64, s52
	s_cselect_b32 s53, s65, s53
	s_cselect_b32 s54, s66, s54
	s_cselect_b32 s55, s67, s55
	v_mov_b64_e32 v[114:115], 0
	v_mov_b64_e32 v[116:117], 0
	v_mov_b64_e32 v[118:119], 0
	v_mov_b64_e32 v[120:121], 0
	v_mov_b64_e32 v[122:123], 0
	v_mov_b64_e32 v[124:125], 0
	v_mov_b64_e32 v[126:127], 0
	v_mov_b64_e32 v[128:129], 0
	v_mov_b64_e32 v[50:51], 0
	v_mov_b64_e32 v[52:53], 0
	v_mov_b64_e32 v[54:55], 0
	v_mov_b64_e32 v[56:57], 0
	v_mov_b64_e32 v[58:59], 0
	v_mov_b64_e32 v[60:61], 0
	v_mov_b64_e32 v[62:63], 0
	v_mov_b64_e32 v[64:65], 0
	v_mov_b64_e32 v[98:99], 0
	v_mov_b64_e32 v[100:101], 0
	v_mov_b64_e32 v[102:103], 0
	v_mov_b64_e32 v[104:105], 0
	v_mov_b64_e32 v[106:107], 0
	v_mov_b64_e32 v[108:109], 0
	v_mov_b64_e32 v[110:111], 0
	v_mov_b64_e32 v[112:113], 0
	v_mov_b64_e32 v[34:35], 0
	v_mov_b64_e32 v[36:37], 0
	v_mov_b64_e32 v[38:39], 0
	v_mov_b64_e32 v[40:41], 0
	v_mov_b64_e32 v[42:43], 0
	v_mov_b64_e32 v[44:45], 0
	v_mov_b64_e32 v[46:47], 0
	v_mov_b64_e32 v[48:49], 0
	v_mov_b64_e32 v[82:83], 0
	v_mov_b64_e32 v[84:85], 0
	v_mov_b64_e32 v[86:87], 0
	v_mov_b64_e32 v[88:89], 0
	v_mov_b64_e32 v[90:91], 0
	v_mov_b64_e32 v[92:93], 0
	v_mov_b64_e32 v[94:95], 0
	v_mov_b64_e32 v[96:97], 0
	v_mov_b64_e32 v[18:19], 0
	v_mov_b64_e32 v[20:21], 0
	v_mov_b64_e32 v[22:23], 0
	v_mov_b64_e32 v[24:25], 0
	v_mov_b64_e32 v[26:27], 0
	v_mov_b64_e32 v[28:29], 0
	v_mov_b64_e32 v[30:31], 0
	v_mov_b64_e32 v[32:33], 0
	v_mov_b64_e32 v[66:67], 0
	v_mov_b64_e32 v[68:69], 0
	v_mov_b64_e32 v[70:71], 0
	v_mov_b64_e32 v[72:73], 0
	v_mov_b64_e32 v[74:75], 0
	v_mov_b64_e32 v[76:77], 0
	v_mov_b64_e32 v[78:79], 0
	v_mov_b64_e32 v[80:81], 0
	v_mov_b64_e32 v[2:3], 0
	v_mov_b64_e32 v[4:5], 0
	v_mov_b64_e32 v[6:7], 0
	v_mov_b64_e32 v[8:9], 0
	v_mov_b64_e32 v[10:11], 0
	v_mov_b64_e32 v[12:13], 0
	v_mov_b64_e32 v[14:15], 0
	v_mov_b64_e32 v[16:17], 0
	s_branch .Lg_inproj_go

; #define MFMA32(a, b, c) __builtin_amdgcn_mfma_f32_32x32x16_bf16((a), (b), (c), 0, 0, 0)
; DI void gemm256(const char* a_u, unsigned a_voff, size_t astep, const char* b_u, unsigned b_voff, size_t bstep, int nk, char* smem, f32x16 (&acc)[4][2]) {
;     ...
;   for (int kt = 0; kt < nk; ++kt) {
;     const int cur = kt & 1, k2 = (kt + 2 < last) ? kt + 2 : last;
;     const char* S = smem + cur * 2 * T2;
;     char* D = smem + (cur ^ 1) * 2 * T2;
;     const char* an = a_u + (size_t)k2 * 128;
;     const char* bn = b_u + (size_t)k2 * 128;
; #pragma unroll
;     for (int s = 0; s < 4; ++s) {
;       bf16x8 a[4], b[2];
; #pragma unroll
;       for (int mi = 0; mi < 4; ++mi) a[mi] = *(const bf16x8*)(S + aoff + mi * 32 * LROW + s * 32);
; #pragma unroll
;       for (int ni = 0; ni < 2; ++ni) b[ni] = *(const bf16x8*)(S + boff + ni * 32 * LROW + s * 32);
;       *(u32x4*)(D + soff + s * 64 * LROW) = ra[s];
;       *(u32x4*)(D + T2 + soff + s * 64 * LROW) = rb[s];
;       ra[s] = *(const u32x4*)(an + s * astep + a_voff);
;       rb[s] = *(const u32x4*)(bn + s * bstep + b_voff);
; #pragma unroll
;       for (int mi = 0; mi < 4; ++mi)
; #pragma unroll
;         for (int ni = 0; ni < 2; ++ni) acc[mi][ni] = MFMA32(a[mi], b[ni], acc[mi][ni]);
;     }
;     __syncthreads();
;   }
.Lg_inproj_go:
	ds_read_b128 v[196:199], v194 offset:0
	ds_read_b128 v[212:215], v160 offset:0
	ds_read_b128 v[216:219], v160 offset:2048
	ds_read_b128 v[242:245], v160 offset:4096
	ds_read_b128 v[246:249], v160 offset:6144
	ds_read_b128 v[200:203], v194 offset:4096
	ds_read_b128 v[204:207], v194 offset:8192
	ds_read_b128 v[208:211], v194 offset:12288
.Lg_inproj_loop:
	s_add_i32 s56, s56, 1
	s_add_u32 m0, s58, 0x8000
	s_nop 0
	global_load_lds_dwordx4 v164, s[52:53]
	s_add_u32 m0, s58, 0x8400
	s_nop 0
	global_load_lds_dwordx4 v165, s[52:53]
	s_add_u32 m0, s58, 0x8800
	s_nop 0
	global_load_lds_dwordx4 v130, s[52:53]
	s_add_u32 m0, s58, 0x8c00
	s_nop 0
	global_load_lds_dwordx4 v131, s[52:53]
	s_add_u32 m0, s59, 0x8000
	s_nop 0
	global_load_lds_dwordx4 v164, s[54:55]
	s_add_u32 m0, s59, 0x8400
	s_nop 0
	global_load_lds_dwordx4 v165, s[54:55]
	s_add_u32 m0, s59, 0x8800
	s_nop 0
	global_load_lds_dwordx4 v130, s[54:55]
	s_add_u32 m0, s59, 0x8c00
	s_nop 0
	global_load_lds_dwordx4 v131, s[54:55]
	s_waitcnt lgkmcnt(0)
	v_mfma_f32_16x16x32_bf16 v[114:117], v[196:199], v[212:215], v[114:117]
	ds_read_b128 v[220:223], v194 offset:2048
	v_mfma_f32_16x16x32_bf16 v[118:121], v[196:199], v[216:219], v[118:121]
	ds_read_b128 v[224:227], v194 offset:6144
	v_mfma_f32_16x16x32_bf16 v[50:53], v[196:199], v[242:245], v[50:53]
	ds_read_b128 v[228:231], v194 offset:10240
	v_mfma_f32_16x16x32_bf16 v[54:57], v[196:199], v[246:249], v[54:57]
	ds_read_b128 v[238:241], v194 offset:14336
	v_mfma_f32_16x16x32_bf16 v[98:101], v[200:203], v[212:215], v[98:101]
	v_mfma_f32_16x16x32_bf16 v[102:105], v[200:203], v[216:219], v[102:105]
	v_mfma_f32_16x16x32_bf16 v[34:37], v[200:203], v[242:245], v[34:37]
	v_mfma_f32_16x16x32_bf16 v[38:41], v[200:203], v[246:249], v[38:41]
	v_mfma_f32_16x16x32_bf16 v[82:85], v[204:207], v[212:215], v[82:85]
	v_mfma_f32_16x16x32_bf16 v[86:89], v[204:207], v[216:219], v[86:89]
	v_mfma_f32_16x16x32_bf16 v[18:21], v[204:207], v[242:245], v[18:21]
	v_mfma_f32_16x16x32_bf16 v[22:25], v[204:207], v[246:249], v[22:25]
	v_mfma_f32_16x16x32_bf16 v[66:69], v[208:211], v[212:215], v[66:69]
	v_mfma_f32_16x16x32_bf16 v[70:73], v[208:211], v[216:219], v[70:73]
	v_mfma_f32_16x16x32_bf16 v[2:5], v[208:211], v[242:245], v[2:5]
	v_mfma_f32_16x16x32_bf16 v[6:9], v[208:211], v[246:249], v[6:9]
	s_waitcnt lgkmcnt(0)
	v_mfma_f32_16x16x32_bf16 v[122:125], v[220:223], v[212:215], v[122:125]
	ds_read_b128 v[196:199], v195 offset:0
	v_mfma_f32_16x16x32_bf16 v[126:129], v[220:223], v[216:219], v[126:129]
	ds_read_b128 v[140:143], v161 offset:0
	v_mfma_f32_16x16x32_bf16 v[58:61], v[220:223], v[242:245], v[58:61]
	ds_read_b128 v[144:147], v161 offset:2048
	v_mfma_f32_16x16x32_bf16 v[62:65], v[220:223], v[246:249], v[62:65]
	ds_read_b128 v[148:151], v161 offset:4096
	v_mfma_f32_16x16x32_bf16 v[106:109], v[224:227], v[212:215], v[106:109]
	ds_read_b128 v[152:155], v161 offset:6144
	v_mfma_f32_16x16x32_bf16 v[110:113], v[224:227], v[216:219], v[110:113]
	ds_read_b128 v[200:203], v195 offset:4096
	v_mfma_f32_16x16x32_bf16 v[42:45], v[224:227], v[242:245], v[42:45]
	ds_read_b128 v[204:207], v195 offset:8192
	v_mfma_f32_16x16x32_bf16 v[46:49], v[224:227], v[246:249], v[46:49]
	ds_read_b128 v[208:211], v195 offset:12288
	v_mfma_f32_16x16x32_bf16 v[90:93], v[228:231], v[212:215], v[90:93]
	v_mfma_f32_16x16x32_bf16 v[94:97], v[228:231], v[216:219], v[94:97]
	v_mfma_f32_16x16x32_bf16 v[26:29], v[228:231], v[242:245], v[26:29]
	v_mfma_f32_16x16x32_bf16 v[30:33], v[228:231], v[246:249], v[30:33]
	v_mfma_f32_16x16x32_bf16 v[74:77], v[238:241], v[212:215], v[74:77]
	v_mfma_f32_16x16x32_bf16 v[78:81], v[238:241], v[216:219], v[78:81]
	v_mfma_f32_16x16x32_bf16 v[10:13], v[238:241], v[242:245], v[10:13]
	v_mfma_f32_16x16x32_bf16 v[14:17], v[238:241], v[246:249], v[14:17]
	s_waitcnt lgkmcnt(0)
	v_mfma_f32_16x16x32_bf16 v[114:117], v[196:199], v[140:143], v[114:117]
	ds_read_b128 v[220:223], v195 offset:2048
	v_mfma_f32_16x16x32_bf16 v[118:121], v[196:199], v[144:147], v[118:121]
	ds_read_b128 v[224:227], v195 offset:6144
	v_mfma_f32_16x16x32_bf16 v[50:53], v[196:199], v[148:151], v[50:53]
	ds_read_b128 v[228:231], v195 offset:10240
	v_mfma_f32_16x16x32_bf16 v[54:57], v[196:199], v[152:155], v[54:57]
	ds_read_b128 v[238:241], v195 offset:14336
	v_mfma_f32_16x16x32_bf16 v[98:101], v[200:203], v[140:143], v[98:101]
	v_mfma_f32_16x16x32_bf16 v[102:105], v[200:203], v[144:147], v[102:105]
	v_mfma_f32_16x16x32_bf16 v[34:37], v[200:203], v[148:151], v[34:37]
	v_mfma_f32_16x16x32_bf16 v[38:41], v[200:203], v[152:155], v[38:41]
	v_mfma_f32_16x16x32_bf16 v[82:85], v[204:207], v[140:143], v[82:85]
	v_mfma_f32_16x16x32_bf16 v[86:89], v[204:207], v[144:147], v[86:89]
	s_cmp_lt_u32 s56, s57
	s_cselect_b32 s60, 0x80, 0
	s_add_u32 s52, s52, s60
	s_addc_u32 s53, s53, 0
	s_add_u32 s54, s54, s60
	s_addc_u32 s55, s55, 0
	s_cmp_eq_u32 s56, s63
	s_cselect_b32 s52, s64, s52
	s_cselect_b32 s53, s65, s53
	s_cselect_b32 s54, s66, s54
	s_cselect_b32 s55, s67, s55
	v_mfma_f32_16x16x32_bf16 v[18:21], v[204:207], v[148:151], v[18:21]
	v_mfma_f32_16x16x32_bf16 v[22:25], v[204:207], v[152:155], v[22:25]
	v_mfma_f32_16x16x32_bf16 v[66:69], v[208:211], v[140:143], v[66:69]
	v_mfma_f32_16x16x32_bf16 v[70:73], v[208:211], v[144:147], v[70:73]
	v_mfma_f32_16x16x32_bf16 v[2:5], v[208:211], v[148:151], v[2:5]
	v_mfma_f32_16x16x32_bf16 v[6:9], v[208:211], v[152:155], v[6:9]
	s_waitcnt lgkmcnt(0)
	v_mfma_f32_16x16x32_bf16 v[122:125], v[220:223], v[140:143], v[122:125]
	v_mfma_f32_16x16x32_bf16 v[126:129], v[220:223], v[144:147], v[126:129]
	v_mfma_f32_16x16x32_bf16 v[58:61], v[220:223], v[148:151], v[58:61]
	v_mfma_f32_16x16x32_bf16 v[62:65], v[220:223], v[152:155], v[62:65]
	v_mfma_f32_16x16x32_bf16 v[106:109], v[224:227], v[140:143], v[106:109]
	v_mfma_f32_16x16x32_bf16 v[110:113], v[224:227], v[144:147], v[110:113]
	v_mfma_f32_16x16x32_bf16 v[42:45], v[224:227], v[148:151], v[42:45]
	v_mfma_f32_16x16x32_bf16 v[46:49], v[224:227], v[152:155], v[46:49]
	v_mfma_f32_16x16x32_bf16 v[90:93], v[228:231], v[140:143], v[90:93]
	v_mfma_f32_16x16x32_bf16 v[94:97], v[228:231], v[144:147], v[94:97]
	v_mfma_f32_16x16x32_bf16 v[26:29], v[228:231], v[148:151], v[26:29]
	v_mfma_f32_16x16x32_bf16 v[30:33], v[228:231], v[152:155], v[30:33]
	v_mfma_f32_16x16x32_bf16 v[74:77], v[238:241], v[140:143], v[74:77]
	v_mfma_f32_16x16x32_bf16 v[78:81], v[238:241], v[144:147], v[78:81]
	v_mfma_f32_16x16x32_bf16 v[10:13], v[238:241], v[148:151], v[10:13]
	v_mfma_f32_16x16x32_bf16 v[14:17], v[238:241], v[152:155], v[14:17]
	s_waitcnt vmcnt(0)
	s_barrier
; #define MFMA32(a, b, c) __builtin_amdgcn_mfma_f32_32x32x16_bf16((a), (b), (c), 0, 0, 0)
; DI void gemm256(const char* a_u, unsigned a_voff, size_t astep, const char* b_u, unsigned b_voff, size_t bstep, int nk, char* smem, f32x16 (&acc)[4][2]) {
;     ...
;   for (int kt = 0; kt < nk; ++kt) {
;     const int cur = kt & 1, k2 = (kt + 2 < last) ? kt + 2 : last;
;     const char* S = smem + cur * 2 * T2;
;     char* D = smem + (cur ^ 1) * 2 * T2;
;     const char* an = a_u + (size_t)k2 * 128;
;     const char* bn = b_u + (size_t)k2 * 128;
; #pragma unroll
;     for (int s = 0; s < 4; ++s) {
;       bf16x8 a[4], b[2];
; #pragma unroll
;       for (int mi = 0; mi < 4; ++mi) a[mi] = *(const bf16x8*)(S + aoff + mi * 32 * LROW + s * 32);
; #pragma unroll
;       for (int ni = 0; ni < 2; ++ni) b[ni] = *(const bf16x8*)(S + boff + ni * 32 * LROW + s * 32);
;       *(u32x4*)(D + soff + s * 64 * LROW) = ra[s];
;       *(u32x4*)(D + T2 + soff + s * 64 * LROW) = rb[s];
;       ra[s] = *(const u32x4*)(an + s * astep + a_voff);
;       rb[s] = *(const u32x4*)(bn + s * bstep + b_voff);
; #pragma unroll
;       for (int mi = 0; mi < 4; ++mi)
; #pragma unroll
;         for (int ni = 0; ni < 2; ++ni) acc[mi][ni] = MFMA32(a[mi], b[ni], acc[mi][ni]);
;     }
;     __syncthreads();
;   }
	ds_read_b128 v[196:199], v194 offset:32768
	ds_read_b128 v[212:215], v160 offset:32768
	ds_read_b128 v[216:219], v160 offset:34816
	ds_read_b128 v[242:245], v160 offset:36864
	ds_read_b128 v[246:249], v160 offset:38912
	ds_read_b128 v[200:203], v194 offset:36864
	ds_read_b128 v[204:207], v194 offset:40960
	ds_read_b128 v[208:211], v194 offset:45056
	s_add_i32 s56, s56, 1
	s_add_u32 m0, s58, 0x0
	s_nop 0
	global_load_lds_dwordx4 v164, s[52:53]
	s_add_u32 m0, s58, 0x400
	s_nop 0
	global_load_lds_dwordx4 v165, s[52:53]
	s_add_u32 m0, s58, 0x800
	s_nop 0
	global_load_lds_dwordx4 v130, s[52:53]
	s_add_u32 m0, s58, 0xc00
	s_nop 0
	global_load_lds_dwordx4 v131, s[52:53]
	s_add_u32 m0, s59, 0x0
	s_nop 0
	global_load_lds_dwordx4 v164, s[54:55]
	s_add_u32 m0, s59, 0x400
	s_nop 0
	global_load_lds_dwordx4 v165, s[54:55]
	s_add_u32 m0, s59, 0x800
	s_nop 0
	global_load_lds_dwordx4 v130, s[54:55]
	s_add_u32 m0, s59, 0xc00
	s_nop 0
	global_load_lds_dwordx4 v131, s[54:55]
	s_waitcnt lgkmcnt(0)
	v_mfma_f32_16x16x32_bf16 v[114:117], v[196:199], v[212:215], v[114:117]
	ds_read_b128 v[220:223], v194 offset:34816
	v_mfma_f32_16x16x32_bf16 v[118:121], v[196:199], v[216:219], v[118:121]
	ds_read_b128 v[224:227], v194 offset:38912
	v_mfma_f32_16x16x32_bf16 v[50:53], v[196:199], v[242:245], v[50:53]
	ds_read_b128 v[228:231], v194 offset:43008
	v_mfma_f32_16x16x32_bf16 v[54:57], v[196:199], v[246:249], v[54:57]
	ds_read_b128 v[238:241], v194 offset:47104
	v_mfma_f32_16x16x32_bf16 v[98:101], v[200:203], v[212:215], v[98:101]
	v_mfma_f32_16x16x32_bf16 v[102:105], v[200:203], v[216:219], v[102:105]
	v_mfma_f32_16x16x32_bf16 v[34:37], v[200:203], v[242:245], v[34:37]
	v_mfma_f32_16x16x32_bf16 v[38:41], v[200:203], v[246:249], v[38:41]
	v_mfma_f32_16x16x32_bf16 v[82:85], v[204:207], v[212:215], v[82:85]
	v_mfma_f32_16x16x32_bf16 v[86:89], v[204:207], v[216:219], v[86:89]
	v_mfma_f32_16x16x32_bf16 v[18:21], v[204:207], v[242:245], v[18:21]
	v_mfma_f32_16x16x32_bf16 v[22:25], v[204:207], v[246:249], v[22:25]
	v_mfma_f32_16x16x32_bf16 v[66:69], v[208:211], v[212:215], v[66:69]
	v_mfma_f32_16x16x32_bf16 v[70:73], v[208:211], v[216:219], v[70:73]
	v_mfma_f32_16x16x32_bf16 v[2:5], v[208:211], v[242:245], v[2:5]
	v_mfma_f32_16x16x32_bf16 v[6:9], v[208:211], v[246:249], v[6:9]
	s_waitcnt lgkmcnt(0)
	v_mfma_f32_16x16x32_bf16 v[122:125], v[220:223], v[212:215], v[122:125]
	ds_read_b128 v[196:199], v195 offset:32768
	v_mfma_f32_16x16x32_bf16 v[126:129], v[220:223], v[216:219], v[126:129]
	ds_read_b128 v[140:143], v161 offset:32768
	v_mfma_f32_16x16x32_bf16 v[58:61], v[220:223], v[242:245], v[58:61]
	ds_read_b128 v[144:147], v161 offset:34816
	v_mfma_f32_16x16x32_bf16 v[62:65], v[220:223], v[246:249], v[62:65]
	ds_read_b128 v[148:151], v161 offset:36864
	v_mfma_f32_16x16x32_bf16 v[106:109], v[224:227], v[212:215], v[106:109]
	ds_read_b128 v[152:155], v161 offset:38912
	v_mfma_f32_16x16x32_bf16 v[110:113], v[224:227], v[216:219], v[110:113]
	ds_read_b128 v[200:203], v195 offset:36864
	v_mfma_f32_16x16x32_bf16 v[42:45], v[224:227], v[242:245], v[42:45]
	ds_read_b128 v[204:207], v195 offset:40960
	v_mfma_f32_16x16x32_bf16 v[46:49], v[224:227], v[246:249], v[46:49]
	ds_read_b128 v[208:211], v195 offset:45056
	v_mfma_f32_16x16x32_bf16 v[90:93], v[228:231], v[212:215], v[90:93]
	v_mfma_f32_16x16x32_bf16 v[94:97], v[228:231], v[216:219], v[94:97]
	v_mfma_f32_16x16x32_bf16 v[26:29], v[228:231], v[242:245], v[26:29]
	v_mfma_f32_16x16x32_bf16 v[30:33], v[228:231], v[246:249], v[30:33]
	v_mfma_f32_16x16x32_bf16 v[74:77], v[238:241], v[212:215], v[74:77]
	v_mfma_f32_16x16x32_bf16 v[78:81], v[238:241], v[216:219], v[78:81]
	v_mfma_f32_16x16x32_bf16 v[10:13], v[238:241], v[242:245], v[10:13]
	v_mfma_f32_16x16x32_bf16 v[14:17], v[238:241], v[246:249], v[14:17]
	s_waitcnt lgkmcnt(0)
	v_mfma_f32_16x16x32_bf16 v[114:117], v[196:199], v[140:143], v[114:117]
	ds_read_b128 v[220:223], v195 offset:34816
	v_mfma_f32_16x16x32_bf16 v[118:121], v[196:199], v[144:147], v[118:121]
	ds_read_b128 v[224:227], v195 offset:38912
	v_mfma_f32_16x16x32_bf16 v[50:53], v[196:199], v[148:151], v[50:53]
	ds_read_b128 v[228:231], v195 offset:43008
	v_mfma_f32_16x16x32_bf16 v[54:57], v[196:199], v[152:155], v[54:57]
	ds_read_b128 v[238:241], v195 offset:47104
	v_mfma_f32_16x16x32_bf16 v[98:101], v[200:203], v[140:143], v[98:101]
	v_mfma_f32_16x16x32_bf16 v[102:105], v[200:203], v[144:147], v[102:105]
	v_mfma_f32_16x16x32_bf16 v[34:37], v[200:203], v[148:151], v[34:37]
	v_mfma_f32_16x16x32_bf16 v[38:41], v[200:203], v[152:155], v[38:41]
	v_mfma_f32_16x16x32_bf16 v[82:85], v[204:207], v[140:143], v[82:85]
	v_mfma_f32_16x16x32_bf16 v[86:89], v[204:207], v[144:147], v[86:89]
	s_cmp_lt_u32 s56, s57
	s_cselect_b32 s60, 0x80, 0
	s_add_u32 s52, s52, s60
	s_addc_u32 s53, s53, 0
	s_add_u32 s54, s54, s60
	s_addc_u32 s55, s55, 0
	s_cmp_eq_u32 s56, s63
	s_cselect_b32 s52, s64, s52
	s_cselect_b32 s53, s65, s53
	s_cselect_b32 s54, s66, s54
	s_cselect_b32 s55, s67, s55
	v_mfma_f32_16x16x32_bf16 v[18:21], v[204:207], v[148:151], v[18:21]
	v_mfma_f32_16x16x32_bf16 v[22:25], v[204:207], v[152:155], v[22:25]
	v_mfma_f32_16x16x32_bf16 v[66:69], v[208:211], v[140:143], v[66:69]
	v_mfma_f32_16x16x32_bf16 v[70:73], v[208:211], v[144:147], v[70:73]
	v_mfma_f32_16x16x32_bf16 v[2:5], v[208:211], v[148:151], v[2:5]
	v_mfma_f32_16x16x32_bf16 v[6:9], v[208:211], v[152:155], v[6:9]
	s_waitcnt lgkmcnt(0)
	v_mfma_f32_16x16x32_bf16 v[122:125], v[220:223], v[140:143], v[122:125]
	v_mfma_f32_16x16x32_bf16 v[126:129], v[220:223], v[144:147], v[126:129]
	v_mfma_f32_16x16x32_bf16 v[58:61], v[220:223], v[148:151], v[58:61]
	v_mfma_f32_16x16x32_bf16 v[62:65], v[220:223], v[152:155], v[62:65]
	v_mfma_f32_16x16x32_bf16 v[106:109], v[224:227], v[140:143], v[106:109]
	v_mfma_f32_16x16x32_bf16 v[110:113], v[224:227], v[144:147], v[110:113]
	v_mfma_f32_16x16x32_bf16 v[42:45], v[224:227], v[148:151], v[42:45]
	v_mfma_f32_16x16x32_bf16 v[46:49], v[224:227], v[152:155], v[46:49]
	v_mfma_f32_16x16x32_bf16 v[90:93], v[228:231], v[140:143], v[90:93]
	v_mfma_f32_16x16x32_bf16 v[94:97], v[228:231], v[144:147], v[94:97]
	v_mfma_f32_16x16x32_bf16 v[26:29], v[228:231], v[148:151], v[26:29]
	v_mfma_f32_16x16x32_bf16 v[30:33], v[228:231], v[152:155], v[30:33]
	v_mfma_f32_16x16x32_bf16 v[74:77], v[238:241], v[140:143], v[74:77]
	v_mfma_f32_16x16x32_bf16 v[78:81], v[238:241], v[144:147], v[78:81]
	v_mfma_f32_16x16x32_bf16 v[10:13], v[238:241], v[148:151], v[10:13]
	v_mfma_f32_16x16x32_bf16 v[14:17], v[238:241], v[152:155], v[14:17]
	s_waitcnt vmcnt(0)
	s_barrier
; #define MFMA32(a, b, c) __builtin_amdgcn_mfma_f32_32x32x16_bf16((a), (b), (c), 0, 0, 0)
; DI void gemm256(const char* a_u, unsigned a_voff, size_t astep, const char* b_u, unsigned b_voff, size_t bstep, int nk, char* smem, f32x16 (&acc)[4][2]) {
;     ...
;   for (int kt = 0; kt < nk; ++kt) {
;     const int cur = kt & 1, k2 = (kt + 2 < last) ? kt + 2 : last;
;     const char* S = smem + cur * 2 * T2;
;     char* D = smem + (cur ^ 1) * 2 * T2;
;     const char* an = a_u + (size_t)k2 * 128;
;     const char* bn = b_u + (size_t)k2 * 128;
; #pragma unroll
;     for (int s = 0; s < 4; ++s) {
;       bf16x8 a[4], b[2];
; #pragma unroll
;       for (int mi = 0; mi < 4; ++mi) a[mi] = *(const bf16x8*)(S + aoff + mi * 32 * LROW + s * 32);
; #pragma unroll
;       for (int ni = 0; ni < 2; ++ni) b[ni] = *(const bf16x8*)(S + boff + ni * 32 * LROW + s * 32);
;       *(u32x4*)(D + soff + s * 64 * LROW) = ra[s];
;       *(u32x4*)(D + T2 + soff + s * 64 * LROW) = rb[s];
;       ra[s] = *(const u32x4*)(an + s * astep + a_voff);
;       rb[s] = *(const u32x4*)(bn + s * bstep + b_voff);
; #pragma unroll
;       for (int mi = 0; mi < 4; ++mi)
; #pragma unroll
;         for (int ni = 0; ni < 2; ++ni) acc[mi][ni] = MFMA32(a[mi], b[ni], acc[mi][ni]);
;     }
;     __syncthreads();
;   }
	ds_read_b128 v[196:199], v194 offset:0
	ds_read_b128 v[212:215], v160 offset:0
	ds_read_b128 v[216:219], v160 offset:2048
	ds_read_b128 v[242:245], v160 offset:4096
	ds_read_b128 v[246:249], v160 offset:6144
	ds_read_b128 v[200:203], v194 offset:4096
	ds_read_b128 v[204:207], v194 offset:8192
	ds_read_b128 v[208:211], v194 offset:12288
	s_cmp_lt_u32 s56, s57
	s_cbranch_scc1 .Lg_inproj_loop
	s_waitcnt vmcnt(0) lgkmcnt(0)
	s_nop 7
	s_nop 7
	v_permlane16_swap_b32_e32 v114, v118
	v_permlane16_swap_b32_e32 v115, v119
	v_permlane16_swap_b32_e32 v116, v120
	v_permlane16_swap_b32_e32 v117, v121
	v_permlane16_swap_b32_e32 v122, v126
	v_permlane16_swap_b32_e32 v123, v127
	v_permlane16_swap_b32_e32 v124, v128
	v_permlane16_swap_b32_e32 v125, v129
	v_permlane16_swap_b32_e32 v50, v54
	v_permlane16_swap_b32_e32 v51, v55
	v_permlane16_swap_b32_e32 v52, v56
	v_permlane16_swap_b32_e32 v53, v57
	v_permlane16_swap_b32_e32 v58, v62
	v_permlane16_swap_b32_e32 v59, v63
	v_permlane16_swap_b32_e32 v60, v64
	v_permlane16_swap_b32_e32 v61, v65
	v_permlane16_swap_b32_e32 v98, v102
	v_permlane16_swap_b32_e32 v99, v103
	v_permlane16_swap_b32_e32 v100, v104
	v_permlane16_swap_b32_e32 v101, v105
	v_permlane16_swap_b32_e32 v106, v110
	v_permlane16_swap_b32_e32 v107, v111
	v_permlane16_swap_b32_e32 v108, v112
	v_permlane16_swap_b32_e32 v109, v113
	v_permlane16_swap_b32_e32 v34, v38
	v_permlane16_swap_b32_e32 v35, v39
	v_permlane16_swap_b32_e32 v36, v40
	v_permlane16_swap_b32_e32 v37, v41
	v_permlane16_swap_b32_e32 v42, v46
	v_permlane16_swap_b32_e32 v43, v47
	v_permlane16_swap_b32_e32 v44, v48
	v_permlane16_swap_b32_e32 v45, v49
	v_permlane16_swap_b32_e32 v82, v86
	v_permlane16_swap_b32_e32 v83, v87
	v_permlane16_swap_b32_e32 v84, v88
	v_permlane16_swap_b32_e32 v85, v89
	v_permlane16_swap_b32_e32 v90, v94
	v_permlane16_swap_b32_e32 v91, v95
	v_permlane16_swap_b32_e32 v92, v96
	v_permlane16_swap_b32_e32 v93, v97
	v_permlane16_swap_b32_e32 v18, v22
	v_permlane16_swap_b32_e32 v19, v23
	v_permlane16_swap_b32_e32 v20, v24
	v_permlane16_swap_b32_e32 v21, v25
	v_permlane16_swap_b32_e32 v26, v30
	v_permlane16_swap_b32_e32 v27, v31
	v_permlane16_swap_b32_e32 v28, v32
	v_permlane16_swap_b32_e32 v29, v33
	v_permlane16_swap_b32_e32 v66, v70
	v_permlane16_swap_b32_e32 v67, v71
	v_permlane16_swap_b32_e32 v68, v72
	v_permlane16_swap_b32_e32 v69, v73
	v_permlane16_swap_b32_e32 v74, v78
	v_permlane16_swap_b32_e32 v75, v79
	v_permlane16_swap_b32_e32 v76, v80
	v_permlane16_swap_b32_e32 v77, v81
	v_permlane16_swap_b32_e32 v2, v6
	v_permlane16_swap_b32_e32 v3, v7
	v_permlane16_swap_b32_e32 v4, v8
	v_permlane16_swap_b32_e32 v5, v9
	v_permlane16_swap_b32_e32 v10, v14
	v_permlane16_swap_b32_e32 v11, v15
	v_permlane16_swap_b32_e32 v12, v16
	v_permlane16_swap_b32_e32 v13, v17
	v_permlane32_swap_b32_e32 v114, v118
	v_permlane32_swap_b32_e32 v115, v119
	v_permlane32_swap_b32_e32 v116, v120
	v_permlane32_swap_b32_e32 v117, v121
	v_permlane32_swap_b32_e32 v122, v126
	v_permlane32_swap_b32_e32 v123, v127
	v_permlane32_swap_b32_e32 v124, v128
	v_permlane32_swap_b32_e32 v125, v129
	v_permlane32_swap_b32_e32 v50, v54
	v_permlane32_swap_b32_e32 v51, v55
	v_permlane32_swap_b32_e32 v52, v56
	v_permlane32_swap_b32_e32 v53, v57
	v_permlane32_swap_b32_e32 v58, v62
	v_permlane32_swap_b32_e32 v59, v63
	v_permlane32_swap_b32_e32 v60, v64
	v_permlane32_swap_b32_e32 v61, v65
	v_permlane32_swap_b32_e32 v98, v102
	v_permlane32_swap_b32_e32 v99, v103
	v_permlane32_swap_b32_e32 v100, v104
	v_permlane32_swap_b32_e32 v101, v105
	v_permlane32_swap_b32_e32 v106, v110
	v_permlane32_swap_b32_e32 v107, v111
	v_permlane32_swap_b32_e32 v108, v112
	v_permlane32_swap_b32_e32 v109, v113
	v_permlane32_swap_b32_e32 v34, v38
	v_permlane32_swap_b32_e32 v35, v39
	v_permlane32_swap_b32_e32 v36, v40
	v_permlane32_swap_b32_e32 v37, v41
	v_permlane32_swap_b32_e32 v42, v46
	v_permlane32_swap_b32_e32 v43, v47
	v_permlane32_swap_b32_e32 v44, v48
	v_permlane32_swap_b32_e32 v45, v49
	v_permlane32_swap_b32_e32 v82, v86
	v_permlane32_swap_b32_e32 v83, v87
	v_permlane32_swap_b32_e32 v84, v88
	v_permlane32_swap_b32_e32 v85, v89
	v_permlane32_swap_b32_e32 v90, v94
	v_permlane32_swap_b32_e32 v91, v95
	v_permlane32_swap_b32_e32 v92, v96
	v_permlane32_swap_b32_e32 v93, v97
	v_permlane32_swap_b32_e32 v18, v22
	v_permlane32_swap_b32_e32 v19, v23
	v_permlane32_swap_b32_e32 v20, v24
	v_permlane32_swap_b32_e32 v21, v25
	v_permlane32_swap_b32_e32 v26, v30
	v_permlane32_swap_b32_e32 v27, v31
	v_permlane32_swap_b32_e32 v28, v32
	v_permlane32_swap_b32_e32 v29, v33
	v_permlane32_swap_b32_e32 v66, v70
	v_permlane32_swap_b32_e32 v67, v71
	v_permlane32_swap_b32_e32 v68, v72
	v_permlane32_swap_b32_e32 v69, v73
	v_permlane32_swap_b32_e32 v74, v78
	v_permlane32_swap_b32_e32 v75, v79
	v_permlane32_swap_b32_e32 v76, v80
	v_permlane32_swap_b32_e32 v77, v81
	v_permlane32_swap_b32_e32 v2, v6
	v_permlane32_swap_b32_e32 v3, v7
	v_permlane32_swap_b32_e32 v4, v8
	v_permlane32_swap_b32_e32 v5, v9
	v_permlane32_swap_b32_e32 v10, v14
	v_permlane32_swap_b32_e32 v11, v15
	v_permlane32_swap_b32_e32 v12, v16
	v_permlane32_swap_b32_e32 v13, v17
	s_nop 1
	s_branch .LBB0_195

; DI void attn_block(const Params& p, int layer, int hd, int q0, int nkeys, char* smem) {
;     ...
;   if (mp == 0) {
;     float ss = 0.f;
; #pragma unroll
;     for (int vt = 0; vt < 4; ++vt)
; #pragma unroll
;       for (int g = 0; g < 4; ++g) {
;         const f32x4 x4 = *(const f32x4*)(Xc + xrow + 32 * vt + 8 * g + 4 * h);
;         o[vt][4 * g] = o[vt][4 * g] * scl - x4.x; o[vt][4 * g + 1] = o[vt][4 * g + 1] * scl - x4.y;
;         o[vt][4 * g + 2] = o[vt][4 * g + 2] * scl - x4.z; o[vt][4 * g + 3] = o[vt][4 * g + 3] * scl - x4.w;
;         ss += o[vt][4 * g] * o[vt][4 * g] + o[vt][4 * g + 1] * o[vt][4 * g + 1] + o[vt][4 * g + 2] * o[vt][4 * g + 2] + o[vt][4 * g + 3] * o[vt][4 * g + 3];
;       }
.LBB0_406:
	s_or_b64 exec, exec, s[4:5]
	s_waitcnt lgkmcnt(0)
	s_barrier
	s_and_saveexec_b64 s[4:5], s[42:43]
	s_cbranch_execz .LBB0_388
	ds_read_b128 v[110:113], v114
	ds_read_b128 v[106:109], v114 offset:32
	ds_read_b128 v[102:105], v114 offset:64
	ds_read_b128 v[98:101], v114 offset:96
	ds_read_b128 v[94:97], v114 offset:128
	ds_read_b128 v[90:93], v114 offset:160
	ds_read_b128 v[86:89], v114 offset:192
	ds_read_b128 v[82:85], v114 offset:224
	ds_read_b128 v[78:81], v114 offset:256
	ds_read_b128 v[74:77], v114 offset:288
	ds_read_b128 v[70:73], v114 offset:320
	ds_read_b128 v[66:69], v114 offset:352
	ds_read_b128 v[126:129], v114 offset:384
	ds_read_b128 v[130:133], v114 offset:416
	v_mov_b32_e32 v117, v54
	v_mov_b32_e32 v54, v51
	v_mov_b32_e32 v116, v50
	s_waitcnt lgkmcnt(1)
	v_mov_b32_e32 v118, v126
	s_waitcnt lgkmcnt(0)
	v_mov_b32_e32 v119, v130
	v_mov_b32_e32 v130, v127
	v_pk_fma_f32 v[122:123], v[54:55], v[124:125], v[130:131] op_sel_hi:[1,0,1] neg_lo:[0,0,1] neg_hi:[0,0,1]
	v_mov_b32_e32 v50, v52
	v_mov_b32_e32 v51, v56
	v_mov_b32_e32 v54, v128
	v_mov_b32_e32 v55, v132
	v_pk_fma_f32 v[120:121], v[116:117], v[124:125], v[118:119] op_sel_hi:[1,0,1] neg_lo:[0,0,1] neg_hi:[0,0,1]
	v_pk_fma_f32 v[118:119], v[50:51], v[124:125], v[54:55] op_sel_hi:[1,0,1] neg_lo:[0,0,1] neg_hi:[0,0,1]
	v_pk_mul_f32 v[50:51], v[122:123], v[122:123]
	v_mov_b32_e32 v56, v53
	v_mov_b32_e32 v132, v129
	v_pk_fma_f32 v[50:51], v[120:121], v[120:121], v[50:51]
	v_pk_fma_f32 v[116:117], v[56:57], v[124:125], v[132:133] op_sel_hi:[1,0,1] neg_lo:[0,0,1] neg_hi:[0,0,1]
	v_pk_fma_f32 v[50:51], v[118:119], v[118:119], v[50:51]
	v_mov_b32_e32 v54, v58
	v_pk_fma_f32 v[126:127], v[116:117], v[116:117], v[50:51]
	ds_read_b128 v[50:53], v114 offset:448
	ds_read_b128 v[128:131], v114 offset:480
	v_mov_b32_e32 v55, v62
	v_mov_b32_e32 v62, v59
	s_lshl_b32 s22, s94, 1
	s_waitcnt lgkmcnt(1)
	v_mov_b32_e32 v56, v50
	s_waitcnt lgkmcnt(0)
	v_mov_b32_e32 v57, v128
	v_mov_b32_e32 v128, v51
	v_pk_fma_f32 v[114:115], v[54:55], v[124:125], v[56:57] op_sel_hi:[1,0,1] neg_lo:[0,0,1] neg_hi:[0,0,1]
	v_pk_fma_f32 v[58:59], v[62:63], v[124:125], v[128:129] op_sel_hi:[1,0,1] neg_lo:[0,0,1] neg_hi:[0,0,1]
	v_mov_b32_e32 v50, v60
	v_mov_b32_e32 v51, v64
	v_mov_b32_e32 v54, v52
	v_mov_b32_e32 v55, v130
	v_pk_fma_f32 v[56:57], v[50:51], v[124:125], v[54:55] op_sel_hi:[1,0,1] neg_lo:[0,0,1] neg_hi:[0,0,1]
	v_pk_mul_f32 v[50:51], v[58:59], v[58:59]
	v_mov_b32_e32 v64, v61
	v_mov_b32_e32 v130, v53
	v_pk_fma_f32 v[50:51], v[114:115], v[114:115], v[50:51]
	v_pk_fma_f32 v[54:55], v[64:65], v[124:125], v[130:131] op_sel_hi:[1,0,1] neg_lo:[0,0,1] neg_hi:[0,0,1]
	v_pk_fma_f32 v[50:51], v[56:57], v[56:57], v[50:51]
	v_pk_fma_f32 v[106:107], v[38:39], v[124:125], v[106:107] op_sel_hi:[1,0,1] neg_lo:[0,0,1] neg_hi:[0,0,1]
	v_pk_fma_f32 v[60:61], v[54:55], v[54:55], v[50:51]
	global_load_dword v50, v181, s[0:1] offset:72
	v_mov_b32_e32 v51, v181
	v_pk_fma_f32 v[102:103], v[42:43], v[124:125], v[102:103] op_sel_hi:[1,0,1] neg_lo:[0,0,1] neg_hi:[0,0,1]
	v_pk_fma_f32 v[38:39], v[48:49], v[124:125], v[100:101] op_sel_hi:[1,0,1] neg_lo:[0,0,1] neg_hi:[0,0,1]
	v_pk_fma_f32 v[42:43], v[46:47], v[124:125], v[98:99] op_sel_hi:[1,0,1] neg_lo:[0,0,1] neg_hi:[0,0,1]
	v_pk_fma_f32 v[46:47], v[28:29], v[124:125], v[88:89] op_sel_hi:[1,0,1] neg_lo:[0,0,1] neg_hi:[0,0,1]
	v_pk_fma_f32 v[48:49], v[26:27], v[124:125], v[86:87] op_sel_hi:[1,0,1] neg_lo:[0,0,1] neg_hi:[0,0,1]
	v_pk_fma_f32 v[28:29], v[32:33], v[124:125], v[84:85] op_sel_hi:[1,0,1] neg_lo:[0,0,1] neg_hi:[0,0,1]
	v_pk_fma_f32 v[32:33], v[30:31], v[124:125], v[82:83] op_sel_hi:[1,0,1] neg_lo:[0,0,1] neg_hi:[0,0,1]
	v_mov_b32_e32 v30, v49
	v_mov_b32_e32 v31, v33
	v_mov_b32_e32 v26, v48
	v_mov_b32_e32 v27, v32
	v_pk_mul_f32 v[30:31], v[30:31], v[30:31]
	v_pk_fma_f32 v[90:91], v[22:23], v[124:125], v[90:91] op_sel_hi:[1,0,1] neg_lo:[0,0,1] neg_hi:[0,0,1]
	v_mov_b32_e32 v22, v46
	v_mov_b32_e32 v23, v28
	v_pk_fma_f32 v[26:27], v[26:27], v[26:27], v[30:31]
	v_pk_fma_f32 v[108:109], v[40:41], v[124:125], v[108:109] op_sel_hi:[1,0,1] neg_lo:[0,0,1] neg_hi:[0,0,1]
	v_pk_fma_f32 v[40:41], v[18:19], v[124:125], v[94:95] op_sel_hi:[1,0,1] neg_lo:[0,0,1] neg_hi:[0,0,1]
	v_pk_fma_f32 v[18:19], v[24:25], v[124:125], v[92:93] op_sel_hi:[1,0,1] neg_lo:[0,0,1] neg_hi:[0,0,1]
	v_mov_b32_e32 v24, v47
	v_mov_b32_e32 v25, v29
	v_pk_fma_f32 v[22:23], v[22:23], v[22:23], v[26:27]
	v_pk_fma_f32 v[30:31], v[2:3], v[124:125], v[78:79] op_sel_hi:[1,0,1] neg_lo:[0,0,1] neg_hi:[0,0,1]
	v_pk_fma_f32 v[82:83], v[24:25], v[24:25], v[22:23]
	v_pk_fma_f32 v[24:25], v[6:7], v[124:125], v[74:75] op_sel_hi:[1,0,1] neg_lo:[0,0,1] neg_hi:[0,0,1]
	v_pk_fma_f32 v[22:23], v[8:9], v[124:125], v[76:77] op_sel_hi:[1,0,1] neg_lo:[0,0,1] neg_hi:[0,0,1]
	v_mov_b32_e32 v8, v31
	v_mov_b32_e32 v9, v25
	v_pk_fma_f32 v[26:27], v[4:5], v[124:125], v[80:81] op_sel_hi:[1,0,1] neg_lo:[0,0,1] neg_hi:[0,0,1]
	v_mov_b32_e32 v6, v30
	v_mov_b32_e32 v7, v24
	v_pk_mul_f32 v[8:9], v[8:9], v[8:9]
	v_mov_b32_e32 v2, v26
	v_mov_b32_e32 v3, v22
	v_pk_fma_f32 v[6:7], v[6:7], v[6:7], v[8:9]
	v_pk_fma_f32 v[10:11], v[10:11], v[124:125], v[70:71] op_sel_hi:[1,0,1] neg_lo:[0,0,1] neg_hi:[0,0,1]
	v_pk_fma_f32 v[2:3], v[2:3], v[2:3], v[6:7]
	v_pk_fma_f32 v[6:7], v[14:15], v[124:125], v[66:67] op_sel_hi:[1,0,1] neg_lo:[0,0,1] neg_hi:[0,0,1]
	v_mov_b32_e32 v4, v27
	v_mov_b32_e32 v5, v23
	v_mov_b32_e32 v66, v11
	v_mov_b32_e32 v67, v7
	v_pk_fma_f32 v[2:3], v[4:5], v[4:5], v[2:3]
	v_pk_fma_f32 v[8:9], v[12:13], v[124:125], v[72:73] op_sel_hi:[1,0,1] neg_lo:[0,0,1] neg_hi:[0,0,1]
	v_pk_fma_f32 v[4:5], v[16:17], v[124:125], v[68:69] op_sel_hi:[1,0,1] neg_lo:[0,0,1] neg_hi:[0,0,1]
; DI void attn_block(const Params& p, int layer, int hd, int q0, int nkeys, char* smem) {
;     ...
;         ss += o[vt][4 * g] * o[vt][4 * g] + o[vt][4 * g + 1] * o[vt][4 * g + 1] + o[vt][4 * g + 2] * o[vt][4 * g + 2] + o[vt][4 * g + 3] * o[vt][4 * g + 3];
;       }
;     ss += __shfl_xor(ss, 32);
;     const float mul = rsqrtf(ss * (1.f / 128.f) + EPS) * (1.f - scal[18 + layer]);
;     bf16_t* Y = (bf16_t*)(p.ws + O_Y) + (size_t)q * DM + 1024 + hd * 128;
;     const float* sg = p.subln + layer * 128;
; #pragma unroll
;     for (int vt = 0; vt < 4; ++vt)
; #pragma unroll
;       for (int g = 0; g < 4; ++g) {
;         const int vv = 32 * vt + 8 * g + 4 * h;
;         const f32x4 gg = *(const f32x4*)(sg + vv);
	v_mov_b32_e32 v16, v10
	v_mov_b32_e32 v17, v6
	v_pk_mul_f32 v[66:67], v[66:67], v[66:67]
	v_pk_fma_f32 v[64:65], v[34:35], v[124:125], v[110:111] op_sel_hi:[1,0,1] neg_lo:[0,0,1] neg_hi:[0,0,1]
	v_mov_b32_e32 v12, v8
	v_mov_b32_e32 v13, v4
	v_pk_fma_f32 v[16:17], v[16:17], v[16:17], v[66:67]
	v_pk_fma_f32 v[36:37], v[36:37], v[124:125], v[112:113] op_sel_hi:[1,0,1] neg_lo:[0,0,1] neg_hi:[0,0,1]
	v_pk_mul_f32 v[110:111], v[64:65], v[64:65]
	v_pk_mul_f32 v[130:131], v[106:107], v[106:107]
	v_mov_b32_e32 v14, v9
	v_mov_b32_e32 v15, v5
	v_pk_fma_f32 v[12:13], v[12:13], v[12:13], v[16:17]
	v_pk_mul_f32 v[112:113], v[36:37], v[36:37]
	v_pk_mul_f32 v[128:129], v[108:109], v[108:109]
	v_pk_fma_f32 v[44:45], v[44:45], v[124:125], v[104:105] op_sel_hi:[1,0,1] neg_lo:[0,0,1] neg_hi:[0,0,1]
	v_pk_mul_f32 v[134:135], v[102:103], v[102:103]
	v_pk_fma_f32 v[12:13], v[14:15], v[14:15], v[12:13]
	v_add_f32_e32 v15, v130, v131
	v_add_f32_e32 v16, v110, v111
	v_pk_mul_f32 v[104:105], v[44:45], v[44:45]
	v_add_f32_e32 v14, v134, v135
	v_add_f32_e32 v15, v128, v15
	v_add_f32_e32 v16, v112, v16
	v_add_f32_e32 v14, v104, v14
	v_add_f32_e32 v15, v129, v15
	v_add_f32_e32 v16, v113, v16
	v_pk_mul_f32 v[98:99], v[42:43], v[42:43]
	v_add_f32_e32 v14, v105, v14
	v_add_f32_e32 v15, v16, v15
	v_pk_mul_f32 v[100:101], v[38:39], v[38:39]
	v_add_f32_e32 v14, v15, v14
	v_add_f32_e32 v15, v98, v99
	s_waitcnt vmcnt(0)
	v_sub_f32_e32 v132, 1.0, v50
	v_lshlrev_b32_e32 v50, 12, v198
	v_lshl_add_u64 v[50:51], s[36:37], 0, v[50:51]
	v_lshl_add_u64 v[62:63], v[50:51], 0, s[22:23]
	global_load_dwordx4 v[50:53], v180, s[44:45]
	global_load_dwordx4 v[208:211], v180, s[44:45] offset:32
	global_load_dwordx4 v[212:215], v180, s[44:45] offset:64
	global_load_dwordx4 v[216:219], v180, s[44:45] offset:96
	global_load_dwordx4 v[220:223], v180, s[44:45] offset:128
	global_load_dwordx4 v[224:227], v180, s[44:45] offset:160
	global_load_dwordx4 v[228:231], v180, s[44:45] offset:192
	global_load_dwordx4 v[140:143], v180, s[44:45] offset:224
	global_load_dwordx4 v[144:147], v180, s[44:45] offset:256
	global_load_dwordx4 v[148:151], v180, s[44:45] offset:288
	global_load_dwordx4 v[152:155], v180, s[44:45] offset:320
	global_load_dwordx4 v[156:159], v180, s[44:45] offset:352
	global_load_dwordx4 v[160:163], v180, s[44:45] offset:384
	global_load_dwordx4 v[240:243], v180, s[44:45] offset:416
	global_load_dwordx4 v[244:247], v180, s[44:45] offset:448
	global_load_dwordx4 v[248:251], v180, s[44:45] offset:480
	v_add_f32_e32 v15, v100, v15
	v_pk_fma_f32 v[20:21], v[20:21], v[124:125], v[96:97] op_sel_hi:[1,0,1] neg_lo:[0,0,1] neg_hi:[0,0,1]
	v_pk_mul_f32 v[94:95], v[40:41], v[40:41]
	v_add_f32_e32 v15, v101, v15
	v_pk_mul_f32 v[96:97], v[20:21], v[20:21]
	v_add_f32_e32 v14, v14, v15
	v_add_f32_e32 v15, v94, v95
	v_add_f32_e32 v15, v96, v15
	v_pk_mul_f32 v[136:137], v[90:91], v[90:91]
	v_add_f32_e32 v15, v97, v15
	v_pk_mul_f32 v[92:93], v[18:19], v[18:19]
	v_add_f32_e32 v14, v14, v15
	v_add_f32_e32 v15, v136, v137
	v_add_f32_e32 v15, v92, v15
	v_add_f32_e32 v15, v93, v15
	v_add_f32_e32 v14, v14, v15
	v_add_f32_e32 v14, v14, v82
	v_add_f32_e32 v14, v14, v83
	v_add_f32_e32 v2, v14, v2
	v_add_f32_e32 v2, v2, v3
	v_add_f32_e32 v2, v2, v12
	v_add_f32_e32 v2, v2, v13
	v_add_f32_e32 v2, v2, v126
	v_add_f32_e32 v2, v2, v127
	v_add_f32_e32 v2, v2, v60
	v_add_f32_e32 v2, v2, v61
	ds_bpermute_b32 v3, v125, v2
	v_lshlrev_b32_e32 v34, 3, v193
	v_mov_b32_e32 v35, v181
	v_lshl_add_u64 v[62:63], v[62:63], 0, v[34:35]
	s_mov_b64 s[6:7], 0x19af8c00
	s_waitcnt lgkmcnt(0)
	v_add_f32_e32 v2, v2, v3
	v_lshl_add_u64 v[34:35], v[62:63], 0, s[6:7]
	v_fmamk_f32 v2, v2, 0x3c000000, v183
	s_mov_b32 s6, 0x800000
	v_cmp_gt_f32_e32 vcc, s6, v2
	v_mul_f32_e32 v3, 0x4b800000, v2
	s_mov_b32 s6, 0x19af8000
	v_cndmask_b32_e32 v2, v2, v3, vcc
	v_rsq_f32_e32 v2, v2
	s_nop 0
	v_mul_f32_e32 v3, 0x45800000, v2
	v_cndmask_b32_e32 v2, v2, v3, vcc
	v_mul_f32_e32 v2, v132, v2
	v_pk_mul_f32 v[12:13], v[64:65], v[2:3] op_sel_hi:[1,0]
	v_pk_mul_f32 v[14:15], v[36:37], v[2:3] op_sel_hi:[1,0]
	v_pk_mul_f32 v[16:17], v[106:107], v[2:3] op_sel_hi:[1,0]
	v_pk_mul_f32 v[10:11], v[10:11], v[2:3] op_sel_hi:[1,0]
	v_pk_mul_f32 v[8:9], v[8:9], v[2:3] op_sel_hi:[1,0]
	v_pk_mul_f32 v[6:7], v[6:7], v[2:3] op_sel_hi:[1,0]
	v_pk_mul_f32 v[4:5], v[4:5], v[2:3] op_sel_hi:[1,0]
	s_waitcnt vmcnt(0)
; DI void attn_block(const Params& p, int layer, int hd, int q0, int nkeys, char* smem) {
;     ...
; #pragma unroll
;     for (int vt = 0; vt < 4; ++vt)
; #pragma unroll
;       for (int g = 0; g < 4; ++g) {
;         const int vv = 32 * vt + 8 * g + 4 * h;
;         const f32x4 gg = *(const f32x4*)(sg + vv);
;         u32x2 ov; ov.x = pack2(o[vt][4 * g] * mul * gg.x, o[vt][4 * g + 1] * mul * gg.y);
;         ov.y = pack2(o[vt][4 * g + 2] * mul * gg.z, o[vt][4 * g + 3] * mul * gg.w);
;         *(u32x2*)(Y + vv) = ov;
;       }
	v_pk_mul_f32 v[12:13], v[50:51], v[12:13]
	v_pk_mul_f32 v[14:15], v[52:53], v[14:15]
	v_cvt_pk_bf16_f32 v12, v12, v13
	v_cvt_pk_bf16_f32 v13, v14, v15
	v_add_co_u32_e32 v14, vcc, s6, v62
	s_nop 1
	v_addc_co_u32_e32 v15, vcc, 0, v63, vcc
	global_store_dwordx2 v[14:15], v[12:13], off offset:3072
	v_mov_b64_e32 v[12:13], v[208:209]
	v_mov_b64_e32 v[14:15], v[210:211]
	v_pk_mul_f32 v[12:13], v[12:13], v[16:17]
	v_pk_mul_f32 v[16:17], v[108:109], v[2:3] op_sel_hi:[1,0]
	v_cvt_pk_bf16_f32 v12, v12, v13
	v_pk_mul_f32 v[14:15], v[14:15], v[16:17]
	v_pk_mul_f32 v[16:17], v[102:103], v[2:3] op_sel_hi:[1,0]
	v_cvt_pk_bf16_f32 v13, v14, v15
	global_store_dwordx2 v[34:35], v[12:13], off offset:16
	v_mov_b64_e32 v[12:13], v[212:213]
	v_mov_b64_e32 v[14:15], v[214:215]
	v_pk_mul_f32 v[12:13], v[12:13], v[16:17]
	v_pk_mul_f32 v[16:17], v[44:45], v[2:3] op_sel_hi:[1,0]
	v_cvt_pk_bf16_f32 v12, v12, v13
	v_pk_mul_f32 v[14:15], v[14:15], v[16:17]
	v_pk_mul_f32 v[16:17], v[42:43], v[2:3] op_sel_hi:[1,0]
	v_cvt_pk_bf16_f32 v13, v14, v15
	global_store_dwordx2 v[34:35], v[12:13], off offset:32
	v_mov_b64_e32 v[12:13], v[216:217]
	v_mov_b64_e32 v[14:15], v[218:219]
	v_pk_mul_f32 v[12:13], v[12:13], v[16:17]
	v_pk_mul_f32 v[16:17], v[38:39], v[2:3] op_sel_hi:[1,0]
	v_cvt_pk_bf16_f32 v12, v12, v13
	v_pk_mul_f32 v[14:15], v[14:15], v[16:17]
	v_pk_mul_f32 v[16:17], v[40:41], v[2:3] op_sel_hi:[1,0]
	v_cvt_pk_bf16_f32 v13, v14, v15
	global_store_dwordx2 v[34:35], v[12:13], off offset:48
	v_mov_b64_e32 v[12:13], v[220:221]
	v_mov_b64_e32 v[14:15], v[222:223]
	v_pk_mul_f32 v[12:13], v[12:13], v[16:17]
	v_pk_mul_f32 v[16:17], v[20:21], v[2:3] op_sel_hi:[1,0]
	v_cvt_pk_bf16_f32 v12, v12, v13
	v_pk_mul_f32 v[14:15], v[14:15], v[16:17]
	v_pk_mul_f32 v[16:17], v[90:91], v[2:3] op_sel_hi:[1,0]
	v_cvt_pk_bf16_f32 v13, v14, v15
	global_store_dwordx2 v[34:35], v[12:13], off offset:64
	v_mov_b64_e32 v[12:13], v[224:225]
	v_mov_b64_e32 v[14:15], v[226:227]
	v_pk_mul_f32 v[12:13], v[12:13], v[16:17]
	v_pk_mul_f32 v[16:17], v[18:19], v[2:3] op_sel_hi:[1,0]
	v_cvt_pk_bf16_f32 v12, v12, v13
	v_pk_mul_f32 v[14:15], v[14:15], v[16:17]
	v_pk_mul_f32 v[16:17], v[48:49], v[2:3] op_sel_hi:[1,0]
	v_cvt_pk_bf16_f32 v13, v14, v15
	global_store_dwordx2 v[34:35], v[12:13], off offset:80
	v_mov_b64_e32 v[12:13], v[228:229]
	v_mov_b64_e32 v[14:15], v[230:231]
	v_pk_mul_f32 v[12:13], v[12:13], v[16:17]
	v_pk_mul_f32 v[16:17], v[46:47], v[2:3] op_sel_hi:[1,0]
	v_cvt_pk_bf16_f32 v12, v12, v13
	v_pk_mul_f32 v[14:15], v[14:15], v[16:17]
	v_pk_mul_f32 v[16:17], v[32:33], v[2:3] op_sel_hi:[1,0]
	v_cvt_pk_bf16_f32 v13, v14, v15
	global_store_dwordx2 v[34:35], v[12:13], off offset:96
	v_mov_b64_e32 v[12:13], v[140:141]
	v_mov_b64_e32 v[14:15], v[142:143]
	v_pk_mul_f32 v[12:13], v[16:17], v[12:13]
	v_pk_mul_f32 v[16:17], v[28:29], v[2:3] op_sel_hi:[1,0]
	v_cvt_pk_bf16_f32 v12, v12, v13
	v_pk_mul_f32 v[14:15], v[16:17], v[14:15]
	v_pk_mul_f32 v[16:17], v[30:31], v[2:3] op_sel_hi:[1,0]
	v_cvt_pk_bf16_f32 v13, v14, v15
	global_store_dwordx2 v[34:35], v[12:13], off offset:112
	v_mov_b64_e32 v[12:13], v[144:145]
	v_mov_b64_e32 v[14:15], v[146:147]
	v_pk_mul_f32 v[12:13], v[16:17], v[12:13]
	v_pk_mul_f32 v[16:17], v[26:27], v[2:3] op_sel_hi:[1,0]
	v_cvt_pk_bf16_f32 v12, v12, v13
	v_pk_mul_f32 v[14:15], v[16:17], v[14:15]
	v_pk_mul_f32 v[16:17], v[24:25], v[2:3] op_sel_hi:[1,0]
	v_cvt_pk_bf16_f32 v13, v14, v15
	global_store_dwordx2 v[34:35], v[12:13], off offset:128
	v_mov_b64_e32 v[12:13], v[148:149]
	v_mov_b64_e32 v[14:15], v[150:151]
	v_pk_mul_f32 v[12:13], v[16:17], v[12:13]
	v_pk_mul_f32 v[16:17], v[22:23], v[2:3] op_sel_hi:[1,0]
	v_cvt_pk_bf16_f32 v12, v12, v13
	v_pk_mul_f32 v[14:15], v[16:17], v[14:15]
	s_nop 0
	v_cvt_pk_bf16_f32 v13, v14, v15
	global_store_dwordx2 v[34:35], v[12:13], off offset:144
	v_mov_b64_e32 v[12:13], v[152:153]
	v_mov_b64_e32 v[14:15], v[154:155]
	v_pk_mul_f32 v[10:11], v[10:11], v[12:13]
	v_pk_mul_f32 v[8:9], v[8:9], v[14:15]
	v_cvt_pk_bf16_f32 v10, v10, v11
	v_cvt_pk_bf16_f32 v11, v8, v9
	global_store_dwordx2 v[34:35], v[10:11], off offset:160
	v_mov_b64_e32 v[8:9], v[156:157]
	v_mov_b64_e32 v[10:11], v[158:159]
	v_pk_mul_f32 v[6:7], v[6:7], v[8:9]
	v_pk_mul_f32 v[4:5], v[4:5], v[10:11]
	v_cvt_pk_bf16_f32 v6, v6, v7
	v_cvt_pk_bf16_f32 v7, v4, v5
	global_store_dwordx2 v[34:35], v[6:7], off offset:176
	v_mov_b32_e32 v8, v120
	v_mov_b32_e32 v9, v122
	v_pk_mul_f32 v[8:9], v[8:9], v[2:3] op_sel_hi:[1,0]
	v_mov_b32_e32 v122, v121
	v_mov_b64_e32 v[4:5], v[160:161]
	v_mov_b64_e32 v[6:7], v[162:163]
	v_pk_mul_f32 v[4:5], v[8:9], v[4:5]
	v_mov_b32_e32 v8, v118
	v_mov_b32_e32 v9, v116
	v_pk_mul_f32 v[8:9], v[8:9], v[2:3] op_sel_hi:[1,0]
	v_cvt_pk_bf16_f32 v4, v4, v5
	v_pk_mul_f32 v[6:7], v[8:9], v[6:7]
	v_pk_mul_f32 v[8:9], v[122:123], v[2:3] op_sel_hi:[1,0]
	v_cvt_pk_bf16_f32 v5, v6, v7
	global_store_dwordx2 v[34:35], v[4:5], off offset:192
	v_mov_b32_e32 v116, v119
	v_mov_b64_e32 v[4:5], v[240:241]
	v_mov_b64_e32 v[6:7], v[242:243]
	v_pk_mul_f32 v[4:5], v[8:9], v[4:5]
	v_pk_mul_f32 v[8:9], v[116:117], v[2:3] op_sel_hi:[1,0]
	v_cvt_pk_bf16_f32 v4, v4, v5
	v_pk_mul_f32 v[6:7], v[8:9], v[6:7]
	v_mov_b32_e32 v8, v114
	v_cvt_pk_bf16_f32 v5, v6, v7
	global_store_dwordx2 v[34:35], v[4:5], off offset:208
	v_mov_b32_e32 v9, v58
	v_pk_mul_f32 v[8:9], v[8:9], v[2:3] op_sel_hi:[1,0]
	v_mov_b32_e32 v58, v115
	v_mov_b64_e32 v[4:5], v[244:245]
	v_mov_b64_e32 v[6:7], v[246:247]
	v_pk_mul_f32 v[4:5], v[8:9], v[4:5]
	v_mov_b32_e32 v8, v56
	v_mov_b32_e32 v9, v54
	v_pk_mul_f32 v[8:9], v[8:9], v[2:3] op_sel_hi:[1,0]
	v_cvt_pk_bf16_f32 v4, v4, v5
	v_pk_mul_f32 v[6:7], v[8:9], v[6:7]
	v_mov_b32_e32 v54, v57
	v_cvt_pk_bf16_f32 v5, v6, v7
	global_store_dwordx2 v[34:35], v[4:5], off offset:224
	v_pk_mul_f32 v[8:9], v[58:59], v[2:3] op_sel_hi:[1,0]
	v_pk_mul_f32 v[2:3], v[54:55], v[2:3] op_sel_hi:[1,0]
	v_mov_b64_e32 v[4:5], v[248:249]
	v_mov_b64_e32 v[6:7], v[250:251]
	v_pk_mul_f32 v[4:5], v[8:9], v[4:5]
	v_pk_mul_f32 v[2:3], v[2:3], v[6:7]
	v_cvt_pk_bf16_f32 v4, v4, v5
	v_cvt_pk_bf16_f32 v5, v2, v3
	global_store_dwordx2 v[34:35], v[4:5], off offset:240
	s_branch .LBB0_388

; DI void attn_block(const Params& p, int layer, int hd, int q0, int nkeys, char* smem) {
;     ...
;   if (mp == 0) {
;     float ss = 0.f;
; #pragma unroll
;     for (int vt = 0; vt < 4; ++vt)
; #pragma unroll
;       for (int g = 0; g < 4; ++g) {
;         const f32x4 x4 = *(const f32x4*)(Xc + xrow + 32 * vt + 8 * g + 4 * h);
;         o[vt][4 * g] = o[vt][4 * g] * scl - x4.x; o[vt][4 * g + 1] = o[vt][4 * g + 1] * scl - x4.y;
;         o[vt][4 * g + 2] = o[vt][4 * g + 2] * scl - x4.z; o[vt][4 * g + 3] = o[vt][4 * g + 3] * scl - x4.w;
;         ss += o[vt][4 * g] * o[vt][4 * g] + o[vt][4 * g + 1] * o[vt][4 * g + 1] + o[vt][4 * g + 2] * o[vt][4 * g + 2] + o[vt][4 * g + 3] * o[vt][4 * g + 3];
;       }
.LBB0_423:
	s_or_b64 exec, exec, s[0:1]
	s_waitcnt lgkmcnt(0)
	s_barrier
	s_and_saveexec_b64 s[0:1], s[44:45]
	s_cbranch_execz .LBB0_409
	ds_read_b128 v[110:113], v114
	ds_read_b128 v[106:109], v114 offset:32
	ds_read_b128 v[102:105], v114 offset:64
	ds_read_b128 v[98:101], v114 offset:96
	ds_read_b128 v[94:97], v114 offset:128
	ds_read_b128 v[90:93], v114 offset:160
	ds_read_b128 v[86:89], v114 offset:192
	ds_read_b128 v[82:85], v114 offset:224
	ds_read_b128 v[78:81], v114 offset:256
	ds_read_b128 v[74:77], v114 offset:288
	ds_read_b128 v[70:73], v114 offset:320
	ds_read_b128 v[66:69], v114 offset:352
	ds_read_b128 v[126:129], v114 offset:384
	ds_read_b128 v[130:133], v114 offset:416
	v_mov_b32_e32 v117, v54
	v_mov_b32_e32 v54, v51
	v_mov_b32_e32 v116, v50
	s_waitcnt lgkmcnt(1)
	v_mov_b32_e32 v118, v126
	s_waitcnt lgkmcnt(0)
	v_mov_b32_e32 v119, v130
	v_mov_b32_e32 v130, v127
	v_pk_fma_f32 v[122:123], v[54:55], v[124:125], v[130:131] op_sel_hi:[1,0,1] neg_lo:[0,0,1] neg_hi:[0,0,1]
	v_mov_b32_e32 v50, v52
	v_mov_b32_e32 v51, v56
	v_mov_b32_e32 v54, v128
	v_mov_b32_e32 v55, v132
	v_pk_fma_f32 v[120:121], v[116:117], v[124:125], v[118:119] op_sel_hi:[1,0,1] neg_lo:[0,0,1] neg_hi:[0,0,1]
	v_pk_fma_f32 v[118:119], v[50:51], v[124:125], v[54:55] op_sel_hi:[1,0,1] neg_lo:[0,0,1] neg_hi:[0,0,1]
	v_pk_mul_f32 v[50:51], v[122:123], v[122:123]
	v_mov_b32_e32 v56, v53
	v_mov_b32_e32 v132, v129
	v_pk_fma_f32 v[50:51], v[120:121], v[120:121], v[50:51]
	v_pk_fma_f32 v[116:117], v[56:57], v[124:125], v[132:133] op_sel_hi:[1,0,1] neg_lo:[0,0,1] neg_hi:[0,0,1]
	v_pk_fma_f32 v[50:51], v[118:119], v[118:119], v[50:51]
	v_mov_b32_e32 v54, v58
	v_pk_fma_f32 v[126:127], v[116:117], v[116:117], v[50:51]
	ds_read_b128 v[50:53], v114 offset:448
	ds_read_b128 v[128:131], v114 offset:480
	v_mov_b32_e32 v55, v62
	v_mov_b32_e32 v62, v59
	v_readlane_b32 s6, v254, 16
	s_waitcnt lgkmcnt(1)
	v_mov_b32_e32 v56, v50
	s_waitcnt lgkmcnt(0)
	v_mov_b32_e32 v57, v128
	v_mov_b32_e32 v128, v51
	v_pk_fma_f32 v[114:115], v[54:55], v[124:125], v[56:57] op_sel_hi:[1,0,1] neg_lo:[0,0,1] neg_hi:[0,0,1]
	v_pk_fma_f32 v[58:59], v[62:63], v[124:125], v[128:129] op_sel_hi:[1,0,1] neg_lo:[0,0,1] neg_hi:[0,0,1]
	v_mov_b32_e32 v50, v60
	v_mov_b32_e32 v51, v64
	v_mov_b32_e32 v54, v52
	v_mov_b32_e32 v55, v130
	v_pk_fma_f32 v[56:57], v[50:51], v[124:125], v[54:55] op_sel_hi:[1,0,1] neg_lo:[0,0,1] neg_hi:[0,0,1]
	v_pk_mul_f32 v[50:51], v[58:59], v[58:59]
	v_mov_b32_e32 v64, v61
	v_mov_b32_e32 v130, v53
	v_pk_fma_f32 v[50:51], v[114:115], v[114:115], v[50:51]
	v_pk_fma_f32 v[54:55], v[64:65], v[124:125], v[130:131] op_sel_hi:[1,0,1] neg_lo:[0,0,1] neg_hi:[0,0,1]
	v_pk_fma_f32 v[50:51], v[56:57], v[56:57], v[50:51]
	v_readlane_b32 s7, v254, 17
	v_pk_fma_f32 v[60:61], v[54:55], v[54:55], v[50:51]
	v_mov_b32_e32 v51, v181
	v_readlane_b32 s52, v252, 18
	v_readlane_b32 s53, v252, 19
	v_pk_fma_f32 v[106:107], v[38:39], v[124:125], v[106:107] op_sel_hi:[1,0,1] neg_lo:[0,0,1] neg_hi:[0,0,1]
	global_load_dword v50, v181, s[6:7]
	v_pk_fma_f32 v[102:103], v[42:43], v[124:125], v[102:103] op_sel_hi:[1,0,1] neg_lo:[0,0,1] neg_hi:[0,0,1]
	v_pk_fma_f32 v[38:39], v[48:49], v[124:125], v[100:101] op_sel_hi:[1,0,1] neg_lo:[0,0,1] neg_hi:[0,0,1]
	v_pk_fma_f32 v[42:43], v[46:47], v[124:125], v[98:99] op_sel_hi:[1,0,1] neg_lo:[0,0,1] neg_hi:[0,0,1]
	v_pk_fma_f32 v[46:47], v[28:29], v[124:125], v[88:89] op_sel_hi:[1,0,1] neg_lo:[0,0,1] neg_hi:[0,0,1]
	v_pk_fma_f32 v[48:49], v[26:27], v[124:125], v[86:87] op_sel_hi:[1,0,1] neg_lo:[0,0,1] neg_hi:[0,0,1]
	v_pk_fma_f32 v[28:29], v[32:33], v[124:125], v[84:85] op_sel_hi:[1,0,1] neg_lo:[0,0,1] neg_hi:[0,0,1]
	v_pk_fma_f32 v[32:33], v[30:31], v[124:125], v[82:83] op_sel_hi:[1,0,1] neg_lo:[0,0,1] neg_hi:[0,0,1]
	v_mov_b32_e32 v30, v49
	v_mov_b32_e32 v31, v33
	v_mov_b32_e32 v26, v48
	v_mov_b32_e32 v27, v32
	v_pk_mul_f32 v[30:31], v[30:31], v[30:31]
	v_pk_fma_f32 v[90:91], v[22:23], v[124:125], v[90:91] op_sel_hi:[1,0,1] neg_lo:[0,0,1] neg_hi:[0,0,1]
	v_mov_b32_e32 v22, v46
	v_mov_b32_e32 v23, v28
	v_pk_fma_f32 v[26:27], v[26:27], v[26:27], v[30:31]
	v_pk_fma_f32 v[108:109], v[40:41], v[124:125], v[108:109] op_sel_hi:[1,0,1] neg_lo:[0,0,1] neg_hi:[0,0,1]
	v_pk_fma_f32 v[40:41], v[18:19], v[124:125], v[94:95] op_sel_hi:[1,0,1] neg_lo:[0,0,1] neg_hi:[0,0,1]
	v_pk_fma_f32 v[18:19], v[24:25], v[124:125], v[92:93] op_sel_hi:[1,0,1] neg_lo:[0,0,1] neg_hi:[0,0,1]
	v_mov_b32_e32 v24, v47
	v_mov_b32_e32 v25, v29
	v_pk_fma_f32 v[22:23], v[22:23], v[22:23], v[26:27]
	v_pk_fma_f32 v[30:31], v[2:3], v[124:125], v[78:79] op_sel_hi:[1,0,1] neg_lo:[0,0,1] neg_hi:[0,0,1]
	v_pk_fma_f32 v[82:83], v[24:25], v[24:25], v[22:23]
	v_pk_fma_f32 v[24:25], v[6:7], v[124:125], v[74:75] op_sel_hi:[1,0,1] neg_lo:[0,0,1] neg_hi:[0,0,1]
	v_pk_fma_f32 v[22:23], v[8:9], v[124:125], v[76:77] op_sel_hi:[1,0,1] neg_lo:[0,0,1] neg_hi:[0,0,1]
	v_mov_b32_e32 v8, v31
	v_mov_b32_e32 v9, v25
	v_pk_fma_f32 v[26:27], v[4:5], v[124:125], v[80:81] op_sel_hi:[1,0,1] neg_lo:[0,0,1] neg_hi:[0,0,1]
	v_mov_b32_e32 v6, v30
	v_mov_b32_e32 v7, v24
	v_pk_mul_f32 v[8:9], v[8:9], v[8:9]
	v_mov_b32_e32 v2, v26
	v_mov_b32_e32 v3, v22
	v_pk_fma_f32 v[6:7], v[6:7], v[6:7], v[8:9]
	v_pk_fma_f32 v[10:11], v[10:11], v[124:125], v[70:71] op_sel_hi:[1,0,1] neg_lo:[0,0,1] neg_hi:[0,0,1]
	v_pk_fma_f32 v[2:3], v[2:3], v[2:3], v[6:7]
	v_pk_fma_f32 v[6:7], v[14:15], v[124:125], v[66:67] op_sel_hi:[1,0,1] neg_lo:[0,0,1] neg_hi:[0,0,1]
	v_mov_b32_e32 v4, v27
	v_mov_b32_e32 v5, v23
	v_mov_b32_e32 v66, v11
	v_mov_b32_e32 v67, v7
	v_pk_fma_f32 v[2:3], v[4:5], v[4:5], v[2:3]
	v_pk_fma_f32 v[8:9], v[12:13], v[124:125], v[72:73] op_sel_hi:[1,0,1] neg_lo:[0,0,1] neg_hi:[0,0,1]
; DI void attn_block(const Params& p, int layer, int hd, int q0, int nkeys, char* smem) {
;     ...
;         ss += o[vt][4 * g] * o[vt][4 * g] + o[vt][4 * g + 1] * o[vt][4 * g + 1] + o[vt][4 * g + 2] * o[vt][4 * g + 2] + o[vt][4 * g + 3] * o[vt][4 * g + 3];
;       }
;     ss += __shfl_xor(ss, 32);
;     const float mul = rsqrtf(ss * (1.f / 128.f) + EPS) * (1.f - scal[18 + layer]);
;     bf16_t* Y = (bf16_t*)(p.ws + O_Y) + (size_t)q * DM + 1024 + hd * 128;
;     const float* sg = p.subln + layer * 128;
; #pragma unroll
;     for (int vt = 0; vt < 4; ++vt)
; #pragma unroll
;       for (int g = 0; g < 4; ++g) {
;         const int vv = 32 * vt + 8 * g + 4 * h;
;         const f32x4 gg = *(const f32x4*)(sg + vv);
	v_pk_fma_f32 v[4:5], v[16:17], v[124:125], v[68:69] op_sel_hi:[1,0,1] neg_lo:[0,0,1] neg_hi:[0,0,1]
	v_mov_b32_e32 v16, v10
	v_mov_b32_e32 v17, v6
	v_pk_mul_f32 v[66:67], v[66:67], v[66:67]
	v_pk_fma_f32 v[64:65], v[34:35], v[124:125], v[110:111] op_sel_hi:[1,0,1] neg_lo:[0,0,1] neg_hi:[0,0,1]
	v_mov_b32_e32 v12, v8
	v_mov_b32_e32 v13, v4
	v_pk_fma_f32 v[16:17], v[16:17], v[16:17], v[66:67]
	v_pk_fma_f32 v[36:37], v[36:37], v[124:125], v[112:113] op_sel_hi:[1,0,1] neg_lo:[0,0,1] neg_hi:[0,0,1]
	v_pk_mul_f32 v[110:111], v[64:65], v[64:65]
	v_pk_mul_f32 v[130:131], v[106:107], v[106:107]
	v_mov_b32_e32 v14, v9
	v_mov_b32_e32 v15, v5
	v_pk_fma_f32 v[12:13], v[12:13], v[12:13], v[16:17]
	v_pk_mul_f32 v[112:113], v[36:37], v[36:37]
	v_pk_mul_f32 v[128:129], v[108:109], v[108:109]
	v_pk_fma_f32 v[44:45], v[44:45], v[124:125], v[104:105] op_sel_hi:[1,0,1] neg_lo:[0,0,1] neg_hi:[0,0,1]
	v_pk_mul_f32 v[134:135], v[102:103], v[102:103]
	v_pk_fma_f32 v[12:13], v[14:15], v[14:15], v[12:13]
	v_add_f32_e32 v15, v130, v131
	v_add_f32_e32 v16, v110, v111
	v_pk_mul_f32 v[104:105], v[44:45], v[44:45]
	v_add_f32_e32 v14, v134, v135
	v_add_f32_e32 v15, v128, v15
	v_add_f32_e32 v16, v112, v16
	v_add_f32_e32 v14, v104, v14
	v_add_f32_e32 v15, v129, v15
	v_add_f32_e32 v16, v113, v16
	v_pk_mul_f32 v[98:99], v[42:43], v[42:43]
	v_add_f32_e32 v14, v105, v14
	v_add_f32_e32 v15, v16, v15
	v_pk_mul_f32 v[100:101], v[38:39], v[38:39]
	v_add_f32_e32 v14, v15, v14
	v_add_f32_e32 v15, v98, v99
	v_add_f32_e32 v15, v100, v15
	s_waitcnt vmcnt(0)
	v_sub_f32_e32 v132, 1.0, v50
	v_lshlrev_b32_e32 v50, 12, v206
	v_lshl_add_u64 v[50:51], s[36:37], 0, v[50:51]
	v_lshl_add_u64 v[62:63], v[50:51], 0, s[22:23]
	global_load_dwordx4 v[50:53], v180, s[52:53]
	global_load_dwordx4 v[208:211], v180, s[52:53] offset:32
	global_load_dwordx4 v[212:215], v180, s[52:53] offset:64
	global_load_dwordx4 v[216:219], v180, s[52:53] offset:96
	global_load_dwordx4 v[220:223], v180, s[52:53] offset:128
	global_load_dwordx4 v[224:227], v180, s[52:53] offset:160
	global_load_dwordx4 v[228:231], v180, s[52:53] offset:192
	global_load_dwordx4 v[140:143], v180, s[52:53] offset:224
	global_load_dwordx4 v[144:147], v180, s[52:53] offset:256
	global_load_dwordx4 v[148:151], v180, s[52:53] offset:288
	global_load_dwordx4 v[152:155], v180, s[52:53] offset:320
	global_load_dwordx4 v[156:159], v180, s[52:53] offset:352
	global_load_dwordx4 v[160:163], v180, s[52:53] offset:384
	global_load_dwordx4 v[240:243], v180, s[52:53] offset:416
	global_load_dwordx4 v[244:247], v180, s[52:53] offset:448
	global_load_dwordx4 v[248:251], v180, s[52:53] offset:480
	v_pk_fma_f32 v[20:21], v[20:21], v[124:125], v[96:97] op_sel_hi:[1,0,1] neg_lo:[0,0,1] neg_hi:[0,0,1]
	v_pk_mul_f32 v[94:95], v[40:41], v[40:41]
	v_add_f32_e32 v15, v101, v15
	v_pk_mul_f32 v[96:97], v[20:21], v[20:21]
	v_add_f32_e32 v14, v14, v15
	v_add_f32_e32 v15, v94, v95
	v_add_f32_e32 v15, v96, v15
	v_pk_mul_f32 v[136:137], v[90:91], v[90:91]
	v_add_f32_e32 v15, v97, v15
	v_pk_mul_f32 v[92:93], v[18:19], v[18:19]
	v_add_f32_e32 v14, v14, v15
	v_add_f32_e32 v15, v136, v137
	v_add_f32_e32 v15, v92, v15
	v_add_f32_e32 v15, v93, v15
	v_add_f32_e32 v14, v14, v15
	v_add_f32_e32 v14, v14, v82
	v_add_f32_e32 v14, v14, v83
	v_add_f32_e32 v2, v14, v2
	v_add_f32_e32 v2, v2, v3
	v_add_f32_e32 v2, v2, v12
	v_add_f32_e32 v2, v2, v13
	v_add_f32_e32 v2, v2, v126
	v_add_f32_e32 v2, v2, v127
	v_add_f32_e32 v2, v2, v60
	v_add_f32_e32 v2, v2, v61
	ds_bpermute_b32 v3, v125, v2
	v_lshlrev_b32_e32 v34, 3, v193
	v_mov_b32_e32 v35, v181
	v_lshl_add_u64 v[62:63], v[62:63], 0, v[34:35]
	s_mov_b64 s[6:7], 0x19af8c00
	s_waitcnt lgkmcnt(0)
	v_add_f32_e32 v2, v2, v3
	v_fmamk_f32 v2, v2, 0x3c000000, v183
	v_cmp_gt_f32_e32 vcc, s94, v2
	v_mul_f32_e32 v3, 0x4b800000, v2
	v_lshl_add_u64 v[34:35], v[62:63], 0, s[6:7]
	v_cndmask_b32_e32 v2, v2, v3, vcc
	v_rsq_f32_e32 v2, v2
	s_mov_b32 s6, 0x19af8000
	v_readlane_b32 s54, v252, 20
	v_readlane_b32 s55, v252, 21
	v_mul_f32_e32 v3, 0x45800000, v2
	v_cndmask_b32_e32 v2, v2, v3, vcc
	v_mul_f32_e32 v2, v132, v2
	v_pk_mul_f32 v[12:13], v[64:65], v[2:3] op_sel_hi:[1,0]
	v_pk_mul_f32 v[14:15], v[36:37], v[2:3] op_sel_hi:[1,0]
	v_pk_mul_f32 v[16:17], v[106:107], v[2:3] op_sel_hi:[1,0]
	v_pk_mul_f32 v[10:11], v[10:11], v[2:3] op_sel_hi:[1,0]
	v_pk_mul_f32 v[8:9], v[8:9], v[2:3] op_sel_hi:[1,0]
	v_pk_mul_f32 v[6:7], v[6:7], v[2:3] op_sel_hi:[1,0]
	v_pk_mul_f32 v[4:5], v[4:5], v[2:3] op_sel_hi:[1,0]
	v_readlane_b32 s56, v252, 22
	v_readlane_b32 s57, v252, 23
	v_readlane_b32 s58, v252, 24
	v_readlane_b32 s59, v252, 25
	v_readlane_b32 s60, v252, 26
	v_readlane_b32 s61, v252, 27
	v_readlane_b32 s62, v252, 28
	v_readlane_b32 s63, v252, 29
	v_readlane_b32 s64, v252, 30
	v_readlane_b32 s65, v252, 31
	v_readlane_b32 s66, v252, 32
	v_readlane_b32 s67, v252, 33
	s_waitcnt vmcnt(0)
; DI void attn_block(const Params& p, int layer, int hd, int q0, int nkeys, char* smem) {
;     ...
; #pragma unroll
;     for (int vt = 0; vt < 4; ++vt)
; #pragma unroll
;       for (int g = 0; g < 4; ++g) {
;         const int vv = 32 * vt + 8 * g + 4 * h;
;         const f32x4 gg = *(const f32x4*)(sg + vv);
;         u32x2 ov; ov.x = pack2(o[vt][4 * g] * mul * gg.x, o[vt][4 * g + 1] * mul * gg.y);
;         ov.y = pack2(o[vt][4 * g + 2] * mul * gg.z, o[vt][4 * g + 3] * mul * gg.w);
;         *(u32x2*)(Y + vv) = ov;
;       }
	v_pk_mul_f32 v[12:13], v[50:51], v[12:13]
	v_pk_mul_f32 v[14:15], v[52:53], v[14:15]
	v_cvt_pk_bf16_f32 v12, v12, v13
	v_cvt_pk_bf16_f32 v13, v14, v15
	v_add_co_u32_e32 v14, vcc, s6, v62
	s_nop 1
	v_addc_co_u32_e32 v15, vcc, 0, v63, vcc
	global_store_dwordx2 v[14:15], v[12:13], off offset:3072
	v_mov_b64_e32 v[12:13], v[208:209]
	v_mov_b64_e32 v[14:15], v[210:211]
	v_pk_mul_f32 v[12:13], v[12:13], v[16:17]
	v_pk_mul_f32 v[16:17], v[108:109], v[2:3] op_sel_hi:[1,0]
	v_cvt_pk_bf16_f32 v12, v12, v13
	v_pk_mul_f32 v[14:15], v[14:15], v[16:17]
	v_pk_mul_f32 v[16:17], v[102:103], v[2:3] op_sel_hi:[1,0]
	v_cvt_pk_bf16_f32 v13, v14, v15
	global_store_dwordx2 v[34:35], v[12:13], off offset:16
	v_mov_b64_e32 v[12:13], v[212:213]
	v_mov_b64_e32 v[14:15], v[214:215]
	v_pk_mul_f32 v[12:13], v[12:13], v[16:17]
	v_pk_mul_f32 v[16:17], v[44:45], v[2:3] op_sel_hi:[1,0]
	v_cvt_pk_bf16_f32 v12, v12, v13
	v_pk_mul_f32 v[14:15], v[14:15], v[16:17]
	v_pk_mul_f32 v[16:17], v[42:43], v[2:3] op_sel_hi:[1,0]
	v_cvt_pk_bf16_f32 v13, v14, v15
	global_store_dwordx2 v[34:35], v[12:13], off offset:32
	v_mov_b64_e32 v[12:13], v[216:217]
	v_mov_b64_e32 v[14:15], v[218:219]
	v_pk_mul_f32 v[12:13], v[12:13], v[16:17]
	v_pk_mul_f32 v[16:17], v[38:39], v[2:3] op_sel_hi:[1,0]
	v_cvt_pk_bf16_f32 v12, v12, v13
	v_pk_mul_f32 v[14:15], v[14:15], v[16:17]
	v_pk_mul_f32 v[16:17], v[40:41], v[2:3] op_sel_hi:[1,0]
	v_cvt_pk_bf16_f32 v13, v14, v15
	global_store_dwordx2 v[34:35], v[12:13], off offset:48
	v_mov_b64_e32 v[12:13], v[220:221]
	v_mov_b64_e32 v[14:15], v[222:223]
	v_pk_mul_f32 v[12:13], v[12:13], v[16:17]
	v_pk_mul_f32 v[16:17], v[20:21], v[2:3] op_sel_hi:[1,0]
	v_cvt_pk_bf16_f32 v12, v12, v13
	v_pk_mul_f32 v[14:15], v[14:15], v[16:17]
	v_pk_mul_f32 v[16:17], v[90:91], v[2:3] op_sel_hi:[1,0]
	v_cvt_pk_bf16_f32 v13, v14, v15
	global_store_dwordx2 v[34:35], v[12:13], off offset:64
	v_mov_b64_e32 v[12:13], v[224:225]
	v_mov_b64_e32 v[14:15], v[226:227]
	v_pk_mul_f32 v[12:13], v[12:13], v[16:17]
	v_pk_mul_f32 v[16:17], v[18:19], v[2:3] op_sel_hi:[1,0]
	v_cvt_pk_bf16_f32 v12, v12, v13
	v_pk_mul_f32 v[14:15], v[14:15], v[16:17]
	v_pk_mul_f32 v[16:17], v[48:49], v[2:3] op_sel_hi:[1,0]
	v_cvt_pk_bf16_f32 v13, v14, v15
	global_store_dwordx2 v[34:35], v[12:13], off offset:80
	v_mov_b64_e32 v[12:13], v[228:229]
	v_mov_b64_e32 v[14:15], v[230:231]
	v_pk_mul_f32 v[12:13], v[12:13], v[16:17]
	v_pk_mul_f32 v[16:17], v[46:47], v[2:3] op_sel_hi:[1,0]
	v_cvt_pk_bf16_f32 v12, v12, v13
	v_pk_mul_f32 v[14:15], v[14:15], v[16:17]
	v_pk_mul_f32 v[16:17], v[32:33], v[2:3] op_sel_hi:[1,0]
	v_cvt_pk_bf16_f32 v13, v14, v15
	global_store_dwordx2 v[34:35], v[12:13], off offset:96
	v_mov_b64_e32 v[12:13], v[140:141]
	v_mov_b64_e32 v[14:15], v[142:143]
	v_pk_mul_f32 v[12:13], v[16:17], v[12:13]
	v_pk_mul_f32 v[16:17], v[28:29], v[2:3] op_sel_hi:[1,0]
	v_cvt_pk_bf16_f32 v12, v12, v13
	v_pk_mul_f32 v[14:15], v[16:17], v[14:15]
	v_pk_mul_f32 v[16:17], v[30:31], v[2:3] op_sel_hi:[1,0]
	v_cvt_pk_bf16_f32 v13, v14, v15
	global_store_dwordx2 v[34:35], v[12:13], off offset:112
	v_mov_b64_e32 v[12:13], v[144:145]
	v_mov_b64_e32 v[14:15], v[146:147]
	v_pk_mul_f32 v[12:13], v[16:17], v[12:13]
	v_pk_mul_f32 v[16:17], v[26:27], v[2:3] op_sel_hi:[1,0]
	v_cvt_pk_bf16_f32 v12, v12, v13
	v_pk_mul_f32 v[14:15], v[16:17], v[14:15]
	v_pk_mul_f32 v[16:17], v[24:25], v[2:3] op_sel_hi:[1,0]
	v_cvt_pk_bf16_f32 v13, v14, v15
	global_store_dwordx2 v[34:35], v[12:13], off offset:128
	v_mov_b64_e32 v[12:13], v[148:149]
	v_mov_b64_e32 v[14:15], v[150:151]
	v_pk_mul_f32 v[12:13], v[16:17], v[12:13]
	v_pk_mul_f32 v[16:17], v[22:23], v[2:3] op_sel_hi:[1,0]
	v_cvt_pk_bf16_f32 v12, v12, v13
	v_pk_mul_f32 v[14:15], v[16:17], v[14:15]
	s_nop 0
	v_cvt_pk_bf16_f32 v13, v14, v15
	global_store_dwordx2 v[34:35], v[12:13], off offset:144
	v_mov_b64_e32 v[12:13], v[152:153]
	v_mov_b64_e32 v[14:15], v[154:155]
	v_pk_mul_f32 v[10:11], v[10:11], v[12:13]
	v_pk_mul_f32 v[8:9], v[8:9], v[14:15]
	v_cvt_pk_bf16_f32 v10, v10, v11
	v_cvt_pk_bf16_f32 v11, v8, v9
	global_store_dwordx2 v[34:35], v[10:11], off offset:160
	v_mov_b64_e32 v[8:9], v[156:157]
	v_mov_b64_e32 v[10:11], v[158:159]
	v_pk_mul_f32 v[6:7], v[6:7], v[8:9]
	v_pk_mul_f32 v[4:5], v[4:5], v[10:11]
	v_cvt_pk_bf16_f32 v6, v6, v7
	v_cvt_pk_bf16_f32 v7, v4, v5
	global_store_dwordx2 v[34:35], v[6:7], off offset:176
	v_mov_b32_e32 v8, v120
	v_mov_b32_e32 v9, v122
	v_pk_mul_f32 v[8:9], v[8:9], v[2:3] op_sel_hi:[1,0]
	v_mov_b32_e32 v122, v121
	v_mov_b64_e32 v[4:5], v[160:161]
	v_mov_b64_e32 v[6:7], v[162:163]
	v_pk_mul_f32 v[4:5], v[8:9], v[4:5]
	v_mov_b32_e32 v8, v118
	v_mov_b32_e32 v9, v116
	v_pk_mul_f32 v[8:9], v[8:9], v[2:3] op_sel_hi:[1,0]
	v_cvt_pk_bf16_f32 v4, v4, v5
	v_pk_mul_f32 v[6:7], v[8:9], v[6:7]
	v_pk_mul_f32 v[8:9], v[122:123], v[2:3] op_sel_hi:[1,0]
	v_cvt_pk_bf16_f32 v5, v6, v7
	global_store_dwordx2 v[34:35], v[4:5], off offset:192
	v_mov_b32_e32 v116, v119
	v_mov_b64_e32 v[4:5], v[240:241]
	v_mov_b64_e32 v[6:7], v[242:243]
	v_pk_mul_f32 v[4:5], v[8:9], v[4:5]
	v_pk_mul_f32 v[8:9], v[116:117], v[2:3] op_sel_hi:[1,0]
	v_cvt_pk_bf16_f32 v4, v4, v5
	v_pk_mul_f32 v[6:7], v[8:9], v[6:7]
	v_mov_b32_e32 v8, v114
	v_cvt_pk_bf16_f32 v5, v6, v7
	global_store_dwordx2 v[34:35], v[4:5], off offset:208
	v_mov_b32_e32 v9, v58
	v_pk_mul_f32 v[8:9], v[8:9], v[2:3] op_sel_hi:[1,0]
	v_mov_b32_e32 v58, v115
	v_mov_b64_e32 v[4:5], v[244:245]
	v_mov_b64_e32 v[6:7], v[246:247]
	v_pk_mul_f32 v[4:5], v[8:9], v[4:5]
	v_mov_b32_e32 v8, v56
	v_mov_b32_e32 v9, v54
	v_pk_mul_f32 v[8:9], v[8:9], v[2:3] op_sel_hi:[1,0]
	v_cvt_pk_bf16_f32 v4, v4, v5
	v_pk_mul_f32 v[6:7], v[8:9], v[6:7]
	v_mov_b32_e32 v54, v57
	v_cvt_pk_bf16_f32 v5, v6, v7
	global_store_dwordx2 v[34:35], v[4:5], off offset:224
	v_pk_mul_f32 v[8:9], v[58:59], v[2:3] op_sel_hi:[1,0]
	v_pk_mul_f32 v[2:3], v[54:55], v[2:3] op_sel_hi:[1,0]
	v_mov_b64_e32 v[4:5], v[248:249]
	v_mov_b64_e32 v[6:7], v[250:251]
	v_pk_mul_f32 v[4:5], v[8:9], v[4:5]
	v_pk_mul_f32 v[2:3], v[2:3], v[6:7]
	v_cvt_pk_bf16_f32 v4, v4, v5
	v_cvt_pk_bf16_f32 v5, v2, v3
	global_store_dwordx2 v[34:35], v[4:5], off offset:240
	s_branch .LBB0_409

; DI int tid512() { int t = threadIdx.x; asm volatile("" : "+v"(t)); return t; }
; DI unsigned voff256(size_t ld) { const int t = tid512(); return (unsigned)(((size_t)(t >> 3) * ld + (t & 7) * 8) * 2); }
; DI void gemm256(const char* a_u, unsigned a_voff, size_t astep, const char* b_u, unsigned b_voff, size_t bstep, int nk, char* smem, f32x16 (&acc)[4][2]) {
;   asm volatile("" : "+s"(nk));
;   const int t = tid512(), lane = t & 63, w = t >> 6, wm = w >> 2, wn = w & 3, r = lane & 31, h = lane >> 5;
;   const int soff = (t >> 3) * LROW + (t & 7) * 16;
;   const int aoff = (128 * wm + r) * LROW + h * 16, boff = T2 + (64 * wn + r) * LROW + h * 16;
;   u32x4 ra[4], rb[4];
; #pragma unroll
;   for (int i = 0; i < 4; ++i) { ra[i] = *(const u32x4*)(a_u + i * astep + a_voff); rb[i] = *(const u32x4*)(b_u + i * bstep + b_voff); }
;   __syncthreads();
; #pragma unroll
;   for (int i = 0; i < 4; ++i) { *(u32x4*)(smem + soff + i * 64 * LROW) = ra[i]; *(u32x4*)(smem + T2 + soff + i * 64 * LROW) = rb[i]; }
;   const int last = nk - 1;
;   {
;     const int k1 = last < 1 ? last : 1;
; #pragma unroll
;     for (int i = 0; i < 4; ++i) { ra[i] = *(const u32x4*)(a_u + i * astep + k1 * 128 + a_voff); rb[i] = *(const u32x4*)(b_u + i * bstep + k1 * 128 + b_voff); }
;   }
;   __syncthreads();
; DI void gateup256(const Params& p, int layer, char* smem) {
;     ...
;   for (int i = 0;; ++i) {
;     const int L = tile_of(i, 32 * 44);
;     if (L < 0) break;
;     int tm, nb; tile_mn(L, 32, 44, tm, nb);
;     const int t = tid512(), lane = t & 63, w = t >> 6, wm = w >> 2, wn = w & 3, r = lane & 31, h = lane >> 5;
;     const unsigned bvo = (unsigned)(((size_t)((t >> 3) & 31) * DM + (t & 7) * 8) * 2 + ((((t >> 3) >> 5) & 1) ? (O_WU - O_WG) : 0));
;     f32x16 acc[4][2]; zero_acc256(acc);
;     gemm256((const char*)(H + (size_t)(256 + tm * 256) * DM), voff256(DM), (size_t)128 * DM, (const char*)(WG + (size_t)(nb * 128) * DM), bvo, (size_t)64 * DM, DM / 64, smem, acc);
.LBB0_1564:
	s_mul_hi_u32 s4, s6, 0xba2e8ba3
	s_lshr_b32 s4, s4, 7
	s_lshl_b32 s5, s4, 2
	s_sub_i32 s7, 32, s5
	s_min_i32 s7, s7, 4
	s_abs_i32 s9, s7
	v_cvt_f32_u32_e32 v2, s9
	s_sub_i32 s10, 0, s9
	s_mulk_i32 s4, 0xff50
	s_add_i32 s4, s4, s6
	v_rcp_iflag_f32_e32 v2, v2
	s_abs_i32 s8, s4
	s_xor_b32 s6, s4, s7
	s_ashr_i32 s6, s6, 31
	v_mul_f32_e32 v2, 0x4f7ffffe, v2
	v_cvt_u32_f32_e32 v2, v2
	v_mov_b32_e32 v193, v0
	v_mov_b32_e32 v37, v181
	v_readfirstlane_b32 s11, v2
	s_mul_i32 s10, s10, s11
	s_mul_hi_u32 s10, s11, s10
	s_add_i32 s11, s11, s10
	s_mul_hi_u32 s10, s8, s11
	s_mul_i32 s11, s10, s9
	s_sub_i32 s8, s8, s11
	s_add_i32 s11, s10, 1
	s_sub_i32 s15, s8, s9
	s_cmp_ge_u32 s8, s9
	s_cselect_b32 s10, s11, s10
	s_cselect_b32 s8, s15, s8
	s_add_i32 s11, s10, 1
	s_cmp_ge_u32 s8, s9
	s_cselect_b32 s8, s11, s10
	s_xor_b32 s8, s8, s6
	s_sub_i32 s6, s8, s6
	s_mul_i32 s7, s6, s7
	s_sub_i32 s4, s4, s7
	s_add_i32 s4, s4, s5
	s_lshl_b32 s4, s4, 8
	s_addk_i32 s4, 0x100
	v_lshlrev_b32_e32 v2, 9, v193
	v_lshlrev_b32_e32 v3, 4, v193
	v_bfe_i32 v4, v193, 8, 1
	s_ashr_i32 s5, s4, 31
	v_and_b32_e32 v2, 0x1f000, v2
	v_and_b32_e32 v3, 0x70, v3
	v_and_b32_e32 v4, 0x2c00000, v4
	s_lshl_b64 s[8:9], s[4:5], 12
	v_or3_b32 v36, v2, v3, v4
	s_add_u32 s8, s92, s8
	v_mov_b32_e32 v2, v0
	s_addc_u32 s9, s93, s9
	s_lshl_b32 s6, s6, 7
	v_lshlrev_b32_e32 v3, 4, v2
	v_and_b32_e32 v3, 0x70, v3
	v_lshlrev_b32_e32 v2, 9, v2
	s_movk_i32 s5, 0xf000
	s_ashr_i32 s7, s6, 31
	v_and_or_b32 v180, v2, s5, v3
	s_lshl_b64 s[10:11], s[6:7], 12
	s_add_u32 s10, s12, s10
	v_lshl_add_u64 v[162:163], s[8:9], 0, v[180:181]
	s_addc_u32 s11, s13, s11
	v_add_co_u32_e32 v12, vcc, s84, v162
	v_lshl_add_u64 v[164:165], s[10:11], 0, v[36:37]
	s_nop 0
	v_addc_co_u32_e32 v13, vcc, 0, v163, vcc
	v_add_co_u32_e32 v16, vcc, s87, v164
	s_mov_b32 s5, 32
	v_mov_b32_e32 v2, v0
	v_addc_co_u32_e32 v17, vcc, 0, v165, vcc
	v_add_co_u32_e32 v20, vcc, s31, v162
	v_lshlrev_b32_e32 v4, 4, v2
	v_and_b32_e32 v38, 0x70, v4
	v_lshrrev_b32_e32 v132, 6, v0
	s_nop 0
	v_readfirstlane_b32 s61, v132
	v_and_b32_e32 v132, 63, v0
	v_and_b32_e32 v133, 15, v132
	v_lshrrev_b32_e32 v136, 4, v132
	v_bfe_u32 v137, v133, 1, 3
	v_lshlrev_b32_e32 v133, 7, v133
	s_lshr_b32 s60, s61, 2
	s_lshl_b32 s60, s60, 14
	s_add_i32 s60, s60, 16
	s_and_b32 s62, s61, 3
	s_lshl_b32 s62, s62, 13
	s_add_i32 s62, s62, 0x10010
	v_add_u32_e32 v194, 0, v136
	v_xor_b32_e32 v194, v194, v137
	v_lshl_add_u32 v194, v194, 4, v133
	v_add_u32_e32 v160, s62, v194
	v_add_u32_e32 v194, s60, v194
	v_add_u32_e32 v195, 4, v136
	v_xor_b32_e32 v195, v195, v137
	v_lshl_add_u32 v195, v195, 4, v133
	v_add_u32_e32 v161, s62, v195
	v_add_u32_e32 v195, s60, v195
	v_lshrrev_b32_e32 v133, 3, v132
	s_mov_b32 s60, 0x1000
	v_mul_lo_u32 v133, v133, s60
	v_and_b32_e32 v136, 7, v132
	v_lshrrev_b32_e32 v137, 4, v132
	v_xor_b32_e32 v164, v137, v136
	v_lshl_add_u32 v164, v164, 4, v133
	v_add_u32_e32 v165, 4, v137
	v_xor_b32_e32 v165, v165, v136
	v_lshl_add_u32 v165, v165, 4, v133
	v_add_u32_e32 v165, 0x8000, v165
	v_xor_b32_e32 v130, v137, v136
	v_lshl_add_u32 v130, v130, 4, v133
	v_add_u32_e32 v130, 0x10000, v130
	v_add_u32_e32 v131, 4, v137
	v_xor_b32_e32 v131, v131, v136
	v_lshl_add_u32 v131, v131, 4, v133
	v_add_u32_e32 v131, 0x18000, v131
	s_mul_i32 s60, s61, 0x20000
	s_add_u32 s52, s8, s60
	s_addc_u32 s53, s9, 0
	s_lshr_b32 s60, s61, 1
	s_mul_i32 s60, s60, 0x20000
	s_and_b32 s62, s61, 1
	s_mul_i32 s62, s62, 0x2c00000
	s_add_u32 s60, s60, s62
	s_add_u32 s54, s10, s60
	s_addc_u32 s55, s11, 0
	s_lshl_b32 s58, s61, 12
	s_add_i32 s58, s58, 16
	s_add_i32 s59, s58, 0x10000
	s_mov_b32 s56, 0
	s_mov_b32 s57, 31
	s_add_u32 s64, s52, 0x0
	s_addc_u32 s65, s53, 0
	s_add_u32 s66, s54, 0x400000
	s_addc_u32 s67, s55, 0
	s_and_b64 s[62:63], exec, s[40:41]
	s_cselect_b32 s62, 0, 1
	s_add_i32 s60, s14, 1
	s_mul_i32 s60, s60, s88
	s_add_i32 s60, s60, s33
	s_cmp_lt_u32 s60, 176
	s_cselect_b32 s63, s57, -1
	s_cmp_eq_u32 s62, 1
	s_cselect_b32 s63, -1, s63
	s_cbranch_scc1 .Lg_gateup_first
	s_cmp_eq_u32 s14, 0
	s_cbranch_scc1 .Lg_gateup_first
	s_cmp_lt_u32 s56, s57
	s_cselect_b32 s60, 0x80, 0
	s_add_u32 s52, s52, s60
	s_addc_u32 s53, s53, 0
	s_add_u32 s54, s54, s60
	s_addc_u32 s55, s55, 0
	s_cmp_eq_u32 s56, s63
	s_cselect_b32 s52, s64, s52
	s_cselect_b32 s53, s65, s53
	s_cselect_b32 s54, s66, s54
	s_cselect_b32 s55, s67, s55
	v_mov_b64_e32 v[114:115], 0
	v_mov_b64_e32 v[116:117], 0
	v_mov_b64_e32 v[118:119], 0
	v_mov_b64_e32 v[120:121], 0
	v_mov_b64_e32 v[122:123], 0
	v_mov_b64_e32 v[124:125], 0
	v_mov_b64_e32 v[126:127], 0
	v_mov_b64_e32 v[128:129], 0
	v_mov_b64_e32 v[98:99], 0
	v_mov_b64_e32 v[100:101], 0
	v_mov_b64_e32 v[102:103], 0
	v_mov_b64_e32 v[104:105], 0
	v_mov_b64_e32 v[106:107], 0
	v_mov_b64_e32 v[108:109], 0
	v_mov_b64_e32 v[110:111], 0
	v_mov_b64_e32 v[112:113], 0
	v_mov_b64_e32 v[82:83], 0
	v_mov_b64_e32 v[84:85], 0
	v_mov_b64_e32 v[86:87], 0
	v_mov_b64_e32 v[88:89], 0
	v_mov_b64_e32 v[90:91], 0
	v_mov_b64_e32 v[92:93], 0
	v_mov_b64_e32 v[94:95], 0
	v_mov_b64_e32 v[96:97], 0
	v_mov_b64_e32 v[66:67], 0
	v_mov_b64_e32 v[68:69], 0
	v_mov_b64_e32 v[70:71], 0
	v_mov_b64_e32 v[72:73], 0
	v_mov_b64_e32 v[74:75], 0
	v_mov_b64_e32 v[76:77], 0
	v_mov_b64_e32 v[78:79], 0
	v_mov_b64_e32 v[80:81], 0
	v_mov_b64_e32 v[50:51], 0
	v_mov_b64_e32 v[52:53], 0
	v_mov_b64_e32 v[54:55], 0
	v_mov_b64_e32 v[56:57], 0
	v_mov_b64_e32 v[58:59], 0
	v_mov_b64_e32 v[60:61], 0
	v_mov_b64_e32 v[62:63], 0
	v_mov_b64_e32 v[64:65], 0
	v_mov_b64_e32 v[34:35], 0
	v_mov_b64_e32 v[36:37], 0
	v_mov_b64_e32 v[38:39], 0
	v_mov_b64_e32 v[40:41], 0
	v_mov_b64_e32 v[42:43], 0
	v_mov_b64_e32 v[44:45], 0
	v_mov_b64_e32 v[46:47], 0
	v_mov_b64_e32 v[48:49], 0
	v_mov_b64_e32 v[18:19], 0
	v_mov_b64_e32 v[20:21], 0
	v_mov_b64_e32 v[22:23], 0
	v_mov_b64_e32 v[24:25], 0
	v_mov_b64_e32 v[26:27], 0
	v_mov_b64_e32 v[28:29], 0
	v_mov_b64_e32 v[30:31], 0
	v_mov_b64_e32 v[32:33], 0
	v_mov_b64_e32 v[2:3], 0
	v_mov_b64_e32 v[4:5], 0
	v_mov_b64_e32 v[6:7], 0
	v_mov_b64_e32 v[8:9], 0
	v_mov_b64_e32 v[10:11], 0
	v_mov_b64_e32 v[12:13], 0
	v_mov_b64_e32 v[14:15], 0
	v_mov_b64_e32 v[16:17], 0
	s_branch .Lg_gateup_go

; #define MFMA32(a, b, c) __builtin_amdgcn_mfma_f32_32x32x16_bf16((a), (b), (c), 0, 0, 0)
; DI void gemm256(const char* a_u, unsigned a_voff, size_t astep, const char* b_u, unsigned b_voff, size_t bstep, int nk, char* smem, f32x16 (&acc)[4][2]) {
;     ...
;   for (int kt = 0; kt < nk; ++kt) {
;     const int cur = kt & 1, k2 = (kt + 2 < last) ? kt + 2 : last;
;     const char* S = smem + cur * 2 * T2;
;     char* D = smem + (cur ^ 1) * 2 * T2;
;     const char* an = a_u + (size_t)k2 * 128;
;     const char* bn = b_u + (size_t)k2 * 128;
; #pragma unroll
;     for (int s = 0; s < 4; ++s) {
;       bf16x8 a[4], b[2];
; #pragma unroll
;       for (int mi = 0; mi < 4; ++mi) a[mi] = *(const bf16x8*)(S + aoff + mi * 32 * LROW + s * 32);
; #pragma unroll
;       for (int ni = 0; ni < 2; ++ni) b[ni] = *(const bf16x8*)(S + boff + ni * 32 * LROW + s * 32);
;       *(u32x4*)(D + soff + s * 64 * LROW) = ra[s];
;       *(u32x4*)(D + T2 + soff + s * 64 * LROW) = rb[s];
;       ra[s] = *(const u32x4*)(an + s * astep + a_voff);
;       rb[s] = *(const u32x4*)(bn + s * bstep + b_voff);
; #pragma unroll
;       for (int mi = 0; mi < 4; ++mi)
; #pragma unroll
;         for (int ni = 0; ni < 2; ++ni) acc[mi][ni] = MFMA32(a[mi], b[ni], acc[mi][ni]);
;     }
;     __syncthreads();
;   }
.Lg_gateup_loop:
	s_add_i32 s56, s56, 1
	s_add_u32 m0, s58, 0x8000
	s_nop 0
	global_load_lds_dwordx4 v164, s[52:53]
	s_add_u32 m0, s58, 0x8400
	s_nop 0
	global_load_lds_dwordx4 v165, s[52:53]
	s_add_u32 m0, s58, 0x8800
	s_nop 0
	global_load_lds_dwordx4 v130, s[52:53]
	s_add_u32 m0, s58, 0x8c00
	s_nop 0
	global_load_lds_dwordx4 v131, s[52:53]
	s_add_u32 m0, s59, 0x8000
	s_nop 0
	global_load_lds_dwordx4 v164, s[54:55]
	s_add_u32 m0, s59, 0x8400
	s_nop 0
	global_load_lds_dwordx4 v165, s[54:55]
	s_add_u32 m0, s59, 0x8800
	s_nop 0
	global_load_lds_dwordx4 v130, s[54:55]
	s_add_u32 m0, s59, 0x8c00
	s_nop 0
	global_load_lds_dwordx4 v131, s[54:55]
	s_waitcnt lgkmcnt(0)
	v_mfma_f32_16x16x32_bf16 v[114:117], v[196:199], v[212:215], v[114:117]
	ds_read_b128 v[220:223], v194 offset:2048
	v_mfma_f32_16x16x32_bf16 v[118:121], v[196:199], v[216:219], v[118:121]
	ds_read_b128 v[224:227], v194 offset:6144
	v_mfma_f32_16x16x32_bf16 v[98:101], v[196:199], v[242:245], v[98:101]
	ds_read_b128 v[228:231], v194 offset:10240
	v_mfma_f32_16x16x32_bf16 v[102:105], v[196:199], v[246:249], v[102:105]
	ds_read_b128 v[238:241], v194 offset:14336
	v_mfma_f32_16x16x32_bf16 v[82:85], v[200:203], v[212:215], v[82:85]
	v_mfma_f32_16x16x32_bf16 v[86:89], v[200:203], v[216:219], v[86:89]
	v_mfma_f32_16x16x32_bf16 v[66:69], v[200:203], v[242:245], v[66:69]
	v_mfma_f32_16x16x32_bf16 v[70:73], v[200:203], v[246:249], v[70:73]
	v_mfma_f32_16x16x32_bf16 v[50:53], v[204:207], v[212:215], v[50:53]
	v_mfma_f32_16x16x32_bf16 v[54:57], v[204:207], v[216:219], v[54:57]
	v_mfma_f32_16x16x32_bf16 v[34:37], v[204:207], v[242:245], v[34:37]
	v_mfma_f32_16x16x32_bf16 v[38:41], v[204:207], v[246:249], v[38:41]
	v_mfma_f32_16x16x32_bf16 v[18:21], v[208:211], v[212:215], v[18:21]
	v_mfma_f32_16x16x32_bf16 v[22:25], v[208:211], v[216:219], v[22:25]
	v_mfma_f32_16x16x32_bf16 v[2:5], v[208:211], v[242:245], v[2:5]
	v_mfma_f32_16x16x32_bf16 v[6:9], v[208:211], v[246:249], v[6:9]
	s_waitcnt lgkmcnt(0)
	v_mfma_f32_16x16x32_bf16 v[122:125], v[220:223], v[212:215], v[122:125]
	ds_read_b128 v[196:199], v195 offset:0
	v_mfma_f32_16x16x32_bf16 v[126:129], v[220:223], v[216:219], v[126:129]
	ds_read_b128 v[140:143], v161 offset:0
	v_mfma_f32_16x16x32_bf16 v[106:109], v[220:223], v[242:245], v[106:109]
	ds_read_b128 v[144:147], v161 offset:2048
	v_mfma_f32_16x16x32_bf16 v[110:113], v[220:223], v[246:249], v[110:113]
	ds_read_b128 v[148:151], v161 offset:4096
	v_mfma_f32_16x16x32_bf16 v[90:93], v[224:227], v[212:215], v[90:93]
	ds_read_b128 v[152:155], v161 offset:6144
	v_mfma_f32_16x16x32_bf16 v[94:97], v[224:227], v[216:219], v[94:97]
	ds_read_b128 v[200:203], v195 offset:4096
	v_mfma_f32_16x16x32_bf16 v[74:77], v[224:227], v[242:245], v[74:77]
	ds_read_b128 v[204:207], v195 offset:8192
	v_mfma_f32_16x16x32_bf16 v[78:81], v[224:227], v[246:249], v[78:81]
	ds_read_b128 v[208:211], v195 offset:12288
	v_mfma_f32_16x16x32_bf16 v[58:61], v[228:231], v[212:215], v[58:61]
	v_mfma_f32_16x16x32_bf16 v[62:65], v[228:231], v[216:219], v[62:65]
	v_mfma_f32_16x16x32_bf16 v[42:45], v[228:231], v[242:245], v[42:45]
	v_mfma_f32_16x16x32_bf16 v[46:49], v[228:231], v[246:249], v[46:49]
	v_mfma_f32_16x16x32_bf16 v[26:29], v[238:241], v[212:215], v[26:29]
	v_mfma_f32_16x16x32_bf16 v[30:33], v[238:241], v[216:219], v[30:33]
	v_mfma_f32_16x16x32_bf16 v[10:13], v[238:241], v[242:245], v[10:13]
	v_mfma_f32_16x16x32_bf16 v[14:17], v[238:241], v[246:249], v[14:17]
	s_waitcnt lgkmcnt(0)
	v_mfma_f32_16x16x32_bf16 v[114:117], v[196:199], v[140:143], v[114:117]
	ds_read_b128 v[220:223], v195 offset:2048
	v_mfma_f32_16x16x32_bf16 v[118:121], v[196:199], v[144:147], v[118:121]
	ds_read_b128 v[224:227], v195 offset:6144
	v_mfma_f32_16x16x32_bf16 v[98:101], v[196:199], v[148:151], v[98:101]
	ds_read_b128 v[228:231], v195 offset:10240
	v_mfma_f32_16x16x32_bf16 v[102:105], v[196:199], v[152:155], v[102:105]
	ds_read_b128 v[238:241], v195 offset:14336
	v_mfma_f32_16x16x32_bf16 v[82:85], v[200:203], v[140:143], v[82:85]
	v_mfma_f32_16x16x32_bf16 v[86:89], v[200:203], v[144:147], v[86:89]
	v_mfma_f32_16x16x32_bf16 v[66:69], v[200:203], v[148:151], v[66:69]
	v_mfma_f32_16x16x32_bf16 v[70:73], v[200:203], v[152:155], v[70:73]
	v_mfma_f32_16x16x32_bf16 v[50:53], v[204:207], v[140:143], v[50:53]
	v_mfma_f32_16x16x32_bf16 v[54:57], v[204:207], v[144:147], v[54:57]
	s_cmp_lt_u32 s56, s57
	s_cselect_b32 s60, 0x80, 0
	s_add_u32 s52, s52, s60
	s_addc_u32 s53, s53, 0
	s_add_u32 s54, s54, s60
	s_addc_u32 s55, s55, 0
	s_cmp_eq_u32 s56, s63
	s_cselect_b32 s52, s64, s52
	s_cselect_b32 s53, s65, s53
	s_cselect_b32 s54, s66, s54
	s_cselect_b32 s55, s67, s55
	v_mfma_f32_16x16x32_bf16 v[34:37], v[204:207], v[148:151], v[34:37]
	v_mfma_f32_16x16x32_bf16 v[38:41], v[204:207], v[152:155], v[38:41]
	v_mfma_f32_16x16x32_bf16 v[18:21], v[208:211], v[140:143], v[18:21]
	v_mfma_f32_16x16x32_bf16 v[22:25], v[208:211], v[144:147], v[22:25]
	v_mfma_f32_16x16x32_bf16 v[2:5], v[208:211], v[148:151], v[2:5]
	v_mfma_f32_16x16x32_bf16 v[6:9], v[208:211], v[152:155], v[6:9]
	s_waitcnt lgkmcnt(0)
	v_mfma_f32_16x16x32_bf16 v[122:125], v[220:223], v[140:143], v[122:125]
	v_mfma_f32_16x16x32_bf16 v[126:129], v[220:223], v[144:147], v[126:129]
	v_mfma_f32_16x16x32_bf16 v[106:109], v[220:223], v[148:151], v[106:109]
	v_mfma_f32_16x16x32_bf16 v[110:113], v[220:223], v[152:155], v[110:113]
	v_mfma_f32_16x16x32_bf16 v[90:93], v[224:227], v[140:143], v[90:93]
	v_mfma_f32_16x16x32_bf16 v[94:97], v[224:227], v[144:147], v[94:97]
	v_mfma_f32_16x16x32_bf16 v[74:77], v[224:227], v[148:151], v[74:77]
	v_mfma_f32_16x16x32_bf16 v[78:81], v[224:227], v[152:155], v[78:81]
	v_mfma_f32_16x16x32_bf16 v[58:61], v[228:231], v[140:143], v[58:61]
	v_mfma_f32_16x16x32_bf16 v[62:65], v[228:231], v[144:147], v[62:65]
	v_mfma_f32_16x16x32_bf16 v[42:45], v[228:231], v[148:151], v[42:45]
	v_mfma_f32_16x16x32_bf16 v[46:49], v[228:231], v[152:155], v[46:49]
	v_mfma_f32_16x16x32_bf16 v[26:29], v[238:241], v[140:143], v[26:29]
	v_mfma_f32_16x16x32_bf16 v[30:33], v[238:241], v[144:147], v[30:33]
	v_mfma_f32_16x16x32_bf16 v[10:13], v[238:241], v[148:151], v[10:13]
	v_mfma_f32_16x16x32_bf16 v[14:17], v[238:241], v[152:155], v[14:17]
	s_waitcnt vmcnt(0)
	s_barrier
; #define MFMA32(a, b, c) __builtin_amdgcn_mfma_f32_32x32x16_bf16((a), (b), (c), 0, 0, 0)
; DI void gemm256(const char* a_u, unsigned a_voff, size_t astep, const char* b_u, unsigned b_voff, size_t bstep, int nk, char* smem, f32x16 (&acc)[4][2]) {
;     ...
;   for (int kt = 0; kt < nk; ++kt) {
;     const int cur = kt & 1, k2 = (kt + 2 < last) ? kt + 2 : last;
;     const char* S = smem + cur * 2 * T2;
;     char* D = smem + (cur ^ 1) * 2 * T2;
;     const char* an = a_u + (size_t)k2 * 128;
;     const char* bn = b_u + (size_t)k2 * 128;
; #pragma unroll
;     for (int s = 0; s < 4; ++s) {
;       bf16x8 a[4], b[2];
; #pragma unroll
;       for (int mi = 0; mi < 4; ++mi) a[mi] = *(const bf16x8*)(S + aoff + mi * 32 * LROW + s * 32);
; #pragma unroll
;       for (int ni = 0; ni < 2; ++ni) b[ni] = *(const bf16x8*)(S + boff + ni * 32 * LROW + s * 32);
;       *(u32x4*)(D + soff + s * 64 * LROW) = ra[s];
;       *(u32x4*)(D + T2 + soff + s * 64 * LROW) = rb[s];
;       ra[s] = *(const u32x4*)(an + s * astep + a_voff);
;       rb[s] = *(const u32x4*)(bn + s * bstep + b_voff);
; #pragma unroll
;       for (int mi = 0; mi < 4; ++mi)
; #pragma unroll
;         for (int ni = 0; ni < 2; ++ni) acc[mi][ni] = MFMA32(a[mi], b[ni], acc[mi][ni]);
;     }
;     __syncthreads();
;   }
	ds_read_b128 v[196:199], v194 offset:32768
	ds_read_b128 v[212:215], v160 offset:32768
	ds_read_b128 v[216:219], v160 offset:34816
	ds_read_b128 v[242:245], v160 offset:36864
	ds_read_b128 v[246:249], v160 offset:38912
	ds_read_b128 v[200:203], v194 offset:36864
	ds_read_b128 v[204:207], v194 offset:40960
	ds_read_b128 v[208:211], v194 offset:45056
	s_add_i32 s56, s56, 1
	s_add_u32 m0, s58, 0x0
	s_nop 0
	global_load_lds_dwordx4 v164, s[52:53]
	s_add_u32 m0, s58, 0x400
	s_nop 0
	global_load_lds_dwordx4 v165, s[52:53]
	s_add_u32 m0, s58, 0x800
	s_nop 0
	global_load_lds_dwordx4 v130, s[52:53]
	s_add_u32 m0, s58, 0xc00
	s_nop 0
	global_load_lds_dwordx4 v131, s[52:53]
	s_add_u32 m0, s59, 0x0
	s_nop 0
	global_load_lds_dwordx4 v164, s[54:55]
	s_add_u32 m0, s59, 0x400
	s_nop 0
	global_load_lds_dwordx4 v165, s[54:55]
	s_add_u32 m0, s59, 0x800
	s_nop 0
	global_load_lds_dwordx4 v130, s[54:55]
	s_add_u32 m0, s59, 0xc00
	s_nop 0
	global_load_lds_dwordx4 v131, s[54:55]
	s_waitcnt lgkmcnt(0)
	v_mfma_f32_16x16x32_bf16 v[114:117], v[196:199], v[212:215], v[114:117]
	ds_read_b128 v[220:223], v194 offset:34816
	v_mfma_f32_16x16x32_bf16 v[118:121], v[196:199], v[216:219], v[118:121]
	ds_read_b128 v[224:227], v194 offset:38912
	v_mfma_f32_16x16x32_bf16 v[98:101], v[196:199], v[242:245], v[98:101]
	ds_read_b128 v[228:231], v194 offset:43008
	v_mfma_f32_16x16x32_bf16 v[102:105], v[196:199], v[246:249], v[102:105]
	ds_read_b128 v[238:241], v194 offset:47104
	v_mfma_f32_16x16x32_bf16 v[82:85], v[200:203], v[212:215], v[82:85]
	v_mfma_f32_16x16x32_bf16 v[86:89], v[200:203], v[216:219], v[86:89]
	v_mfma_f32_16x16x32_bf16 v[66:69], v[200:203], v[242:245], v[66:69]
	v_mfma_f32_16x16x32_bf16 v[70:73], v[200:203], v[246:249], v[70:73]
	v_mfma_f32_16x16x32_bf16 v[50:53], v[204:207], v[212:215], v[50:53]
	v_mfma_f32_16x16x32_bf16 v[54:57], v[204:207], v[216:219], v[54:57]
	v_mfma_f32_16x16x32_bf16 v[34:37], v[204:207], v[242:245], v[34:37]
	v_mfma_f32_16x16x32_bf16 v[38:41], v[204:207], v[246:249], v[38:41]
	v_mfma_f32_16x16x32_bf16 v[18:21], v[208:211], v[212:215], v[18:21]
	v_mfma_f32_16x16x32_bf16 v[22:25], v[208:211], v[216:219], v[22:25]
	v_mfma_f32_16x16x32_bf16 v[2:5], v[208:211], v[242:245], v[2:5]
	v_mfma_f32_16x16x32_bf16 v[6:9], v[208:211], v[246:249], v[6:9]
	s_waitcnt lgkmcnt(0)
	v_mfma_f32_16x16x32_bf16 v[122:125], v[220:223], v[212:215], v[122:125]
	ds_read_b128 v[196:199], v195 offset:32768
	v_mfma_f32_16x16x32_bf16 v[126:129], v[220:223], v[216:219], v[126:129]
	ds_read_b128 v[140:143], v161 offset:32768
	v_mfma_f32_16x16x32_bf16 v[106:109], v[220:223], v[242:245], v[106:109]
	ds_read_b128 v[144:147], v161 offset:34816
	v_mfma_f32_16x16x32_bf16 v[110:113], v[220:223], v[246:249], v[110:113]
	ds_read_b128 v[148:151], v161 offset:36864
	v_mfma_f32_16x16x32_bf16 v[90:93], v[224:227], v[212:215], v[90:93]
	ds_read_b128 v[152:155], v161 offset:38912
	v_mfma_f32_16x16x32_bf16 v[94:97], v[224:227], v[216:219], v[94:97]
	ds_read_b128 v[200:203], v195 offset:36864
	v_mfma_f32_16x16x32_bf16 v[74:77], v[224:227], v[242:245], v[74:77]
	ds_read_b128 v[204:207], v195 offset:40960
	v_mfma_f32_16x16x32_bf16 v[78:81], v[224:227], v[246:249], v[78:81]
	ds_read_b128 v[208:211], v195 offset:45056
	v_mfma_f32_16x16x32_bf16 v[58:61], v[228:231], v[212:215], v[58:61]
	v_mfma_f32_16x16x32_bf16 v[62:65], v[228:231], v[216:219], v[62:65]
	v_mfma_f32_16x16x32_bf16 v[42:45], v[228:231], v[242:245], v[42:45]
	v_mfma_f32_16x16x32_bf16 v[46:49], v[228:231], v[246:249], v[46:49]
	v_mfma_f32_16x16x32_bf16 v[26:29], v[238:241], v[212:215], v[26:29]
	v_mfma_f32_16x16x32_bf16 v[30:33], v[238:241], v[216:219], v[30:33]
	v_mfma_f32_16x16x32_bf16 v[10:13], v[238:241], v[242:245], v[10:13]
	v_mfma_f32_16x16x32_bf16 v[14:17], v[238:241], v[246:249], v[14:17]
	s_waitcnt lgkmcnt(0)
	v_mfma_f32_16x16x32_bf16 v[114:117], v[196:199], v[140:143], v[114:117]
	ds_read_b128 v[220:223], v195 offset:34816
	v_mfma_f32_16x16x32_bf16 v[118:121], v[196:199], v[144:147], v[118:121]
	ds_read_b128 v[224:227], v195 offset:38912
	v_mfma_f32_16x16x32_bf16 v[98:101], v[196:199], v[148:151], v[98:101]
	ds_read_b128 v[228:231], v195 offset:43008
	v_mfma_f32_16x16x32_bf16 v[102:105], v[196:199], v[152:155], v[102:105]
	ds_read_b128 v[238:241], v195 offset:47104
	v_mfma_f32_16x16x32_bf16 v[82:85], v[200:203], v[140:143], v[82:85]
	v_mfma_f32_16x16x32_bf16 v[86:89], v[200:203], v[144:147], v[86:89]
	v_mfma_f32_16x16x32_bf16 v[66:69], v[200:203], v[148:151], v[66:69]
	v_mfma_f32_16x16x32_bf16 v[70:73], v[200:203], v[152:155], v[70:73]
	v_mfma_f32_16x16x32_bf16 v[50:53], v[204:207], v[140:143], v[50:53]
	v_mfma_f32_16x16x32_bf16 v[54:57], v[204:207], v[144:147], v[54:57]
	s_cmp_lt_u32 s56, s57
	s_cselect_b32 s60, 0x80, 0
	s_add_u32 s52, s52, s60
	s_addc_u32 s53, s53, 0
	s_add_u32 s54, s54, s60
	s_addc_u32 s55, s55, 0
	s_cmp_eq_u32 s56, s63
	s_cselect_b32 s52, s64, s52
	s_cselect_b32 s53, s65, s53
	s_cselect_b32 s54, s66, s54
	s_cselect_b32 s55, s67, s55
	v_mfma_f32_16x16x32_bf16 v[34:37], v[204:207], v[148:151], v[34:37]
	v_mfma_f32_16x16x32_bf16 v[38:41], v[204:207], v[152:155], v[38:41]
	v_mfma_f32_16x16x32_bf16 v[18:21], v[208:211], v[140:143], v[18:21]
	v_mfma_f32_16x16x32_bf16 v[22:25], v[208:211], v[144:147], v[22:25]
	v_mfma_f32_16x16x32_bf16 v[2:5], v[208:211], v[148:151], v[2:5]
	v_mfma_f32_16x16x32_bf16 v[6:9], v[208:211], v[152:155], v[6:9]
	s_waitcnt lgkmcnt(0)
	v_mfma_f32_16x16x32_bf16 v[122:125], v[220:223], v[140:143], v[122:125]
	v_mfma_f32_16x16x32_bf16 v[126:129], v[220:223], v[144:147], v[126:129]
	v_mfma_f32_16x16x32_bf16 v[106:109], v[220:223], v[148:151], v[106:109]
	v_mfma_f32_16x16x32_bf16 v[110:113], v[220:223], v[152:155], v[110:113]
	v_mfma_f32_16x16x32_bf16 v[90:93], v[224:227], v[140:143], v[90:93]
	v_mfma_f32_16x16x32_bf16 v[94:97], v[224:227], v[144:147], v[94:97]
	v_mfma_f32_16x16x32_bf16 v[74:77], v[224:227], v[148:151], v[74:77]
	v_mfma_f32_16x16x32_bf16 v[78:81], v[224:227], v[152:155], v[78:81]
	v_mfma_f32_16x16x32_bf16 v[58:61], v[228:231], v[140:143], v[58:61]
	v_mfma_f32_16x16x32_bf16 v[62:65], v[228:231], v[144:147], v[62:65]
	v_mfma_f32_16x16x32_bf16 v[42:45], v[228:231], v[148:151], v[42:45]
	v_mfma_f32_16x16x32_bf16 v[46:49], v[228:231], v[152:155], v[46:49]
	v_mfma_f32_16x16x32_bf16 v[26:29], v[238:241], v[140:143], v[26:29]
	v_mfma_f32_16x16x32_bf16 v[30:33], v[238:241], v[144:147], v[30:33]
	v_mfma_f32_16x16x32_bf16 v[10:13], v[238:241], v[148:151], v[10:13]
	v_mfma_f32_16x16x32_bf16 v[14:17], v[238:241], v[152:155], v[14:17]
	s_waitcnt vmcnt(0)
	s_barrier
; #define MFMA32(a, b, c) __builtin_amdgcn_mfma_f32_32x32x16_bf16((a), (b), (c), 0, 0, 0)
; DI void gemm256(const char* a_u, unsigned a_voff, size_t astep, const char* b_u, unsigned b_voff, size_t bstep, int nk, char* smem, f32x16 (&acc)[4][2]) {
;     ...
;   for (int kt = 0; kt < nk; ++kt) {
;     const int cur = kt & 1, k2 = (kt + 2 < last) ? kt + 2 : last;
;     const char* S = smem + cur * 2 * T2;
;     char* D = smem + (cur ^ 1) * 2 * T2;
;     const char* an = a_u + (size_t)k2 * 128;
;     const char* bn = b_u + (size_t)k2 * 128;
; #pragma unroll
;     for (int s = 0; s < 4; ++s) {
;       bf16x8 a[4], b[2];
; #pragma unroll
;       for (int mi = 0; mi < 4; ++mi) a[mi] = *(const bf16x8*)(S + aoff + mi * 32 * LROW + s * 32);
; #pragma unroll
;       for (int ni = 0; ni < 2; ++ni) b[ni] = *(const bf16x8*)(S + boff + ni * 32 * LROW + s * 32);
;       *(u32x4*)(D + soff + s * 64 * LROW) = ra[s];
;       *(u32x4*)(D + T2 + soff + s * 64 * LROW) = rb[s];
;       ra[s] = *(const u32x4*)(an + s * astep + a_voff);
;       rb[s] = *(const u32x4*)(bn + s * bstep + b_voff);
; #pragma unroll
;       for (int mi = 0; mi < 4; ++mi)
; #pragma unroll
;         for (int ni = 0; ni < 2; ++ni) acc[mi][ni] = MFMA32(a[mi], b[ni], acc[mi][ni]);
;     }
;     __syncthreads();
;   }
	ds_read_b128 v[196:199], v194 offset:0
	ds_read_b128 v[212:215], v160 offset:0
	ds_read_b128 v[216:219], v160 offset:2048
	ds_read_b128 v[242:245], v160 offset:4096
	ds_read_b128 v[246:249], v160 offset:6144
	ds_read_b128 v[200:203], v194 offset:4096
	ds_read_b128 v[204:207], v194 offset:8192
	ds_read_b128 v[208:211], v194 offset:12288
	s_cmp_lt_u32 s56, s57
	s_cbranch_scc1 .Lg_gateup_loop
	s_waitcnt vmcnt(0) lgkmcnt(0)
	s_nop 7
	s_nop 7
	v_permlane16_swap_b32_e32 v114, v118
	v_permlane16_swap_b32_e32 v115, v119
	v_permlane16_swap_b32_e32 v116, v120
	v_permlane16_swap_b32_e32 v117, v121
	v_permlane16_swap_b32_e32 v122, v126
	v_permlane16_swap_b32_e32 v123, v127
	v_permlane16_swap_b32_e32 v124, v128
	v_permlane16_swap_b32_e32 v125, v129
	v_permlane16_swap_b32_e32 v98, v102
	v_permlane16_swap_b32_e32 v99, v103
	v_permlane16_swap_b32_e32 v100, v104
	v_permlane16_swap_b32_e32 v101, v105
	v_permlane16_swap_b32_e32 v106, v110
	v_permlane16_swap_b32_e32 v107, v111
	v_permlane16_swap_b32_e32 v108, v112
	v_permlane16_swap_b32_e32 v109, v113
	v_permlane16_swap_b32_e32 v82, v86
	v_permlane16_swap_b32_e32 v83, v87
	v_permlane16_swap_b32_e32 v84, v88
	v_permlane16_swap_b32_e32 v85, v89
	v_permlane16_swap_b32_e32 v90, v94
	v_permlane16_swap_b32_e32 v91, v95
	v_permlane16_swap_b32_e32 v92, v96
	v_permlane16_swap_b32_e32 v93, v97
	v_permlane16_swap_b32_e32 v66, v70
	v_permlane16_swap_b32_e32 v67, v71
	v_permlane16_swap_b32_e32 v68, v72
	v_permlane16_swap_b32_e32 v69, v73
	v_permlane16_swap_b32_e32 v74, v78
	v_permlane16_swap_b32_e32 v75, v79
	v_permlane16_swap_b32_e32 v76, v80
	v_permlane16_swap_b32_e32 v77, v81
	v_permlane16_swap_b32_e32 v50, v54
	v_permlane16_swap_b32_e32 v51, v55
	v_permlane16_swap_b32_e32 v52, v56
	v_permlane16_swap_b32_e32 v53, v57
	v_permlane16_swap_b32_e32 v58, v62
	v_permlane16_swap_b32_e32 v59, v63
	v_permlane16_swap_b32_e32 v60, v64
	v_permlane16_swap_b32_e32 v61, v65
	v_permlane16_swap_b32_e32 v34, v38
	v_permlane16_swap_b32_e32 v35, v39
	v_permlane16_swap_b32_e32 v36, v40
	v_permlane16_swap_b32_e32 v37, v41
	v_permlane16_swap_b32_e32 v42, v46
	v_permlane16_swap_b32_e32 v43, v47
	v_permlane16_swap_b32_e32 v44, v48
	v_permlane16_swap_b32_e32 v45, v49
	v_permlane16_swap_b32_e32 v18, v22
	v_permlane16_swap_b32_e32 v19, v23
	v_permlane16_swap_b32_e32 v20, v24
	v_permlane16_swap_b32_e32 v21, v25
	v_permlane16_swap_b32_e32 v26, v30
	v_permlane16_swap_b32_e32 v27, v31
	v_permlane16_swap_b32_e32 v28, v32
	v_permlane16_swap_b32_e32 v29, v33
	v_permlane16_swap_b32_e32 v2, v6
	v_permlane16_swap_b32_e32 v3, v7
	v_permlane16_swap_b32_e32 v4, v8
	v_permlane16_swap_b32_e32 v5, v9
	v_permlane16_swap_b32_e32 v10, v14
	v_permlane16_swap_b32_e32 v11, v15
	v_permlane16_swap_b32_e32 v12, v16
	v_permlane16_swap_b32_e32 v13, v17
	v_permlane32_swap_b32_e32 v114, v118
	v_permlane32_swap_b32_e32 v115, v119
	v_permlane32_swap_b32_e32 v116, v120
	v_permlane32_swap_b32_e32 v117, v121
	v_permlane32_swap_b32_e32 v122, v126
	v_permlane32_swap_b32_e32 v123, v127
	v_permlane32_swap_b32_e32 v124, v128
	v_permlane32_swap_b32_e32 v125, v129
	v_permlane32_swap_b32_e32 v98, v102
	v_permlane32_swap_b32_e32 v99, v103
	v_permlane32_swap_b32_e32 v100, v104
	v_permlane32_swap_b32_e32 v101, v105
	v_permlane32_swap_b32_e32 v106, v110
	v_permlane32_swap_b32_e32 v107, v111
	v_permlane32_swap_b32_e32 v108, v112
	v_permlane32_swap_b32_e32 v109, v113
	v_permlane32_swap_b32_e32 v82, v86
	v_permlane32_swap_b32_e32 v83, v87
	v_permlane32_swap_b32_e32 v84, v88
	v_permlane32_swap_b32_e32 v85, v89
	v_permlane32_swap_b32_e32 v90, v94
	v_permlane32_swap_b32_e32 v91, v95
	v_permlane32_swap_b32_e32 v92, v96
	v_permlane32_swap_b32_e32 v93, v97
	v_permlane32_swap_b32_e32 v66, v70
	v_permlane32_swap_b32_e32 v67, v71
	v_permlane32_swap_b32_e32 v68, v72
	v_permlane32_swap_b32_e32 v69, v73
	v_permlane32_swap_b32_e32 v74, v78
	v_permlane32_swap_b32_e32 v75, v79
	v_permlane32_swap_b32_e32 v76, v80
	v_permlane32_swap_b32_e32 v77, v81
	v_permlane32_swap_b32_e32 v50, v54
	v_permlane32_swap_b32_e32 v51, v55
	v_permlane32_swap_b32_e32 v52, v56
	v_permlane32_swap_b32_e32 v53, v57
	v_permlane32_swap_b32_e32 v58, v62
	v_permlane32_swap_b32_e32 v59, v63
	v_permlane32_swap_b32_e32 v60, v64
	v_permlane32_swap_b32_e32 v61, v65
	v_permlane32_swap_b32_e32 v34, v38
	v_permlane32_swap_b32_e32 v35, v39
	v_permlane32_swap_b32_e32 v36, v40
	v_permlane32_swap_b32_e32 v37, v41
	v_permlane32_swap_b32_e32 v42, v46
	v_permlane32_swap_b32_e32 v43, v47
	v_permlane32_swap_b32_e32 v44, v48
	v_permlane32_swap_b32_e32 v45, v49
	v_permlane32_swap_b32_e32 v18, v22
	v_permlane32_swap_b32_e32 v19, v23
	v_permlane32_swap_b32_e32 v20, v24
	v_permlane32_swap_b32_e32 v21, v25
	v_permlane32_swap_b32_e32 v26, v30
	v_permlane32_swap_b32_e32 v27, v31
	v_permlane32_swap_b32_e32 v28, v32
	v_permlane32_swap_b32_e32 v29, v33
	v_permlane32_swap_b32_e32 v2, v6
	v_permlane32_swap_b32_e32 v3, v7
	v_permlane32_swap_b32_e32 v4, v8
	v_permlane32_swap_b32_e32 v5, v9
	v_permlane32_swap_b32_e32 v10, v14
	v_permlane32_swap_b32_e32 v11, v15
	v_permlane32_swap_b32_e32 v12, v16
	v_permlane32_swap_b32_e32 v13, v17
	s_nop 1
	s_branch .LBB0_1568

; DI int tid512() { int t = threadIdx.x; asm volatile("" : "+v"(t)); return t; }
; DI unsigned voff256(size_t ld) { const int t = tid512(); return (unsigned)(((size_t)(t >> 3) * ld + (t & 7) * 8) * 2); }
; DI void gemm256(const char* a_u, unsigned a_voff, size_t astep, const char* b_u, unsigned b_voff, size_t bstep, int nk, char* smem, f32x16 (&acc)[4][2]) {
;   asm volatile("" : "+s"(nk));
;   const int t = tid512(), lane = t & 63, w = t >> 6, wm = w >> 2, wn = w & 3, r = lane & 31, h = lane >> 5;
;   const int soff = (t >> 3) * LROW + (t & 7) * 16;
;   const int aoff = (128 * wm + r) * LROW + h * 16, boff = T2 + (64 * wn + r) * LROW + h * 16;
;   u32x4 ra[4], rb[4];
; #pragma unroll
;   for (int i = 0; i < 4; ++i) { ra[i] = *(const u32x4*)(a_u + i * astep + a_voff); rb[i] = *(const u32x4*)(b_u + i * bstep + b_voff); }
;   __syncthreads();
; #pragma unroll
;   for (int i = 0; i < 4; ++i) { *(u32x4*)(smem + soff + i * 64 * LROW) = ra[i]; *(u32x4*)(smem + T2 + soff + i * 64 * LROW) = rb[i]; }
;   const int last = nk - 1;
;   {
;     const int k1 = last < 1 ? last : 1;
; #pragma unroll
;     for (int i = 0; i < 4; ++i) { ra[i] = *(const u32x4*)(a_u + i * astep + k1 * 128 + a_voff); rb[i] = *(const u32x4*)(b_u + i * bstep + k1 * 128 + b_voff); }
;   }
;   __syncthreads();
; DI void down256(const Params& p, int layer, char* smem) {
;     ...
;   for (int i = 0;; ++i) {
;     const int L = tile_of(i, 32 * 8);
;     if (L < 0) break;
;     int tm, tn; tile_mn(L, 32, 8, tm, tn);
;     f32x16 acc[4][2]; zero_acc256(acc);
;     gemm256((const char*)(HID + (size_t)(256 + tm * 256) * DFF), voff256(DFF), (size_t)128 * DFF, (const char*)(W + (size_t)(tn * 256) * DFF), voff256(DFF), (size_t)128 * DFF, DFF / 64, smem, acc);
.LBB0_1642:
	s_lshr_b32 s4, s6, 3
	s_and_b32 s4, s4, 0xffffffc
	s_sub_i32 s5, 32, s4
	s_min_i32 s5, s5, 4
	s_abs_i32 s11, s5
	v_cvt_f32_u32_e32 v2, s11
	s_sub_i32 s12, 0, s11
	s_and_b32 s7, s6, 31
	s_ashr_i32 s6, s5, 31
	v_rcp_iflag_f32_e32 v2, v2
	v_mov_b32_e32 v37, v181
	v_mul_f32_e32 v2, 0x4f7ffffe, v2
	v_cvt_u32_f32_e32 v2, v2
	s_nop 0
	v_readfirstlane_b32 s13, v2
	s_mul_i32 s12, s12, s13
	s_mul_hi_u32 s12, s13, s12
	s_add_i32 s13, s13, s12
	s_mul_hi_u32 s12, s7, s13
	s_mul_i32 s13, s12, s11
	s_sub_i32 s13, s7, s13
	s_add_i32 s14, s12, 1
	s_sub_i32 s15, s13, s11
	s_cmp_ge_u32 s13, s11
	s_cselect_b32 s12, s14, s12
	s_cselect_b32 s13, s15, s13
	s_add_i32 s14, s12, 1
	s_cmp_ge_u32 s13, s11
	s_cselect_b32 s11, s14, s12
	s_xor_b32 s11, s11, s6
	s_sub_i32 s6, s11, s6
	s_mul_i32 s5, s6, s5
	s_sub_i32 s5, s7, s5
	v_mov_b32_e32 v2, v0
	s_add_i32 s5, s5, s4
	s_lshl_b32 s11, s5, 8
	v_lshrrev_b32_e32 v3, 3, v2
	v_lshlrev_b32_e32 v2, 3, v2
	v_mul_lo_u32 v3, v3, s34
	s_addk_i32 s11, 0x100
	v_and_or_b32 v2, v2, 56, v3
	s_mul_i32 s4, s11, 0x2c00
	v_readlane_b32 s12, v254, 34
	v_lshlrev_b32_e32 v180, 1, v2
	v_mov_b32_e32 v2, v0
	s_mul_hi_u32 s5, s11, 0x2c00
	v_readlane_b32 s13, v254, 35
	s_add_u32 s4, s12, s4
	s_addc_u32 s5, s13, s5
	v_lshrrev_b32_e32 v3, 3, v2
	s_lshl_b32 s12, s6, 8
	s_mul_i32 s6, s6, 0x2c0000
	v_lshlrev_b32_e32 v2, 3, v2
	v_mul_lo_u32 v3, v3, s34
	s_mul_hi_i32 s7, s12, 0x2c00
	s_add_u32 s6, s8, s6
	v_and_or_b32 v2, v2, 56, v3
	v_lshl_add_u64 v[162:163], s[4:5], 0, v[180:181]
	s_addc_u32 s7, s9, s7
	v_lshlrev_b32_e32 v36, 1, v2
	v_add_co_u32_e32 v12, vcc, s26, v162
	v_lshl_add_u64 v[164:165], s[6:7], 0, v[36:37]
	s_nop 0
	v_addc_co_u32_e32 v13, vcc, 0, v163, vcc
	v_add_co_u32_e32 v16, vcc, s26, v164
	s_movk_i32 s13, 0x58
	v_mov_b32_e32 v2, v0
	v_addc_co_u32_e32 v17, vcc, 0, v165, vcc
	v_add_co_u32_e32 v20, vcc, s86, v162
	v_lshlrev_b32_e32 v4, 4, v2
	v_and_b32_e32 v38, 0x70, v4
	v_lshrrev_b32_e32 v132, 6, v0
	s_nop 0
	v_readfirstlane_b32 s61, v132
	v_and_b32_e32 v132, 63, v0
	v_and_b32_e32 v133, 15, v132
	v_lshrrev_b32_e32 v136, 4, v132
	v_bfe_u32 v137, v133, 1, 3
	v_lshlrev_b32_e32 v133, 7, v133
	s_lshr_b32 s60, s61, 2
	s_lshl_b32 s60, s60, 14
	s_add_i32 s60, s60, 16
	s_and_b32 s62, s61, 3
	s_lshl_b32 s62, s62, 13
	s_add_i32 s62, s62, 0x10010
	v_add_u32_e32 v194, 0, v136
	v_xor_b32_e32 v194, v194, v137
	v_lshl_add_u32 v194, v194, 4, v133
	v_add_u32_e32 v160, s62, v194
	v_add_u32_e32 v194, s60, v194
	v_add_u32_e32 v195, 4, v136
	v_xor_b32_e32 v195, v195, v137
	v_lshl_add_u32 v195, v195, 4, v133
	v_add_u32_e32 v161, s62, v195
	v_add_u32_e32 v195, s60, v195
	v_lshrrev_b32_e32 v133, 3, v132
	s_mov_b32 s60, 0x2c00
	v_mul_lo_u32 v133, v133, s60
	v_and_b32_e32 v136, 7, v132
	v_lshrrev_b32_e32 v137, 4, v132
	v_xor_b32_e32 v164, v137, v136
	v_lshl_add_u32 v164, v164, 4, v133
	v_add_u32_e32 v165, 4, v137
	v_xor_b32_e32 v165, v165, v136
	v_lshl_add_u32 v165, v165, 4, v133
	v_add_u32_e32 v165, 0x16000, v165
	v_xor_b32_e32 v130, v137, v136
	v_lshl_add_u32 v130, v130, 4, v133
	v_add_u32_e32 v130, 0x2c000, v130
	v_add_u32_e32 v131, 4, v137
	v_xor_b32_e32 v131, v131, v136
	v_lshl_add_u32 v131, v131, 4, v133
	v_add_u32_e32 v131, 0x42000, v131
	s_mul_i32 s60, s61, 0x58000
	s_add_u32 s52, s4, s60
	s_addc_u32 s53, s5, 0
	s_add_u32 s54, s6, s60
	s_addc_u32 s55, s7, 0
	s_lshl_b32 s58, s61, 12
	s_add_i32 s58, s58, 16
	s_add_i32 s59, s58, 0x10000
	s_mov_b32 s56, 0
	s_mov_b32 s57, 87
	s_barrier
	s_add_u32 m0, s58, 0x0
	s_nop 0
	global_load_lds_dwordx4 v164, s[52:53]
	s_add_u32 m0, s58, 0x400
	s_nop 0
	global_load_lds_dwordx4 v165, s[52:53]
	s_add_u32 m0, s58, 0x800
	s_nop 0
	global_load_lds_dwordx4 v130, s[52:53]
	s_add_u32 m0, s58, 0xc00
	s_nop 0
	global_load_lds_dwordx4 v131, s[52:53]
	s_add_u32 m0, s59, 0x0
	s_nop 0
	global_load_lds_dwordx4 v164, s[54:55]
	s_add_u32 m0, s59, 0x400
	s_nop 0
	global_load_lds_dwordx4 v165, s[54:55]
	s_add_u32 m0, s59, 0x800
	s_nop 0
	global_load_lds_dwordx4 v130, s[54:55]
	s_add_u32 m0, s59, 0xc00
	s_nop 0
	global_load_lds_dwordx4 v131, s[54:55]
	s_cmp_lt_u32 s56, s57
	s_cselect_b32 s60, 0x80, 0
	s_add_u32 s52, s52, s60
	s_addc_u32 s53, s53, 0
	s_add_u32 s54, s54, s60
	s_addc_u32 s55, s55, 0
	v_mov_b64_e32 v[114:115], 0
	v_mov_b64_e32 v[116:117], 0
	v_mov_b64_e32 v[118:119], 0
	v_mov_b64_e32 v[120:121], 0
	v_mov_b64_e32 v[122:123], 0
	v_mov_b64_e32 v[124:125], 0
	v_mov_b64_e32 v[126:127], 0
	v_mov_b64_e32 v[128:129], 0
	v_mov_b64_e32 v[98:99], 0
	v_mov_b64_e32 v[100:101], 0
	v_mov_b64_e32 v[102:103], 0
	v_mov_b64_e32 v[104:105], 0
	v_mov_b64_e32 v[106:107], 0
	v_mov_b64_e32 v[108:109], 0
	v_mov_b64_e32 v[110:111], 0
	v_mov_b64_e32 v[112:113], 0
	v_mov_b64_e32 v[82:83], 0
	v_mov_b64_e32 v[84:85], 0
	v_mov_b64_e32 v[86:87], 0
	v_mov_b64_e32 v[88:89], 0
	v_mov_b64_e32 v[90:91], 0
	v_mov_b64_e32 v[92:93], 0
	v_mov_b64_e32 v[94:95], 0
	v_mov_b64_e32 v[96:97], 0
	v_mov_b64_e32 v[66:67], 0
	v_mov_b64_e32 v[68:69], 0
	v_mov_b64_e32 v[70:71], 0
	v_mov_b64_e32 v[72:73], 0
	v_mov_b64_e32 v[74:75], 0
	v_mov_b64_e32 v[76:77], 0
	v_mov_b64_e32 v[78:79], 0
	v_mov_b64_e32 v[80:81], 0
	v_mov_b64_e32 v[50:51], 0
	v_mov_b64_e32 v[52:53], 0
	v_mov_b64_e32 v[54:55], 0
	v_mov_b64_e32 v[56:57], 0
	v_mov_b64_e32 v[58:59], 0
	v_mov_b64_e32 v[60:61], 0
	v_mov_b64_e32 v[62:63], 0
	v_mov_b64_e32 v[64:65], 0
	v_mov_b64_e32 v[34:35], 0
	v_mov_b64_e32 v[36:37], 0
	v_mov_b64_e32 v[38:39], 0
	v_mov_b64_e32 v[40:41], 0
	v_mov_b64_e32 v[42:43], 0
	v_mov_b64_e32 v[44:45], 0
	v_mov_b64_e32 v[46:47], 0
	v_mov_b64_e32 v[48:49], 0
	v_mov_b64_e32 v[18:19], 0
	v_mov_b64_e32 v[20:21], 0
	v_mov_b64_e32 v[22:23], 0
	v_mov_b64_e32 v[24:25], 0
	v_mov_b64_e32 v[26:27], 0
	v_mov_b64_e32 v[28:29], 0
	v_mov_b64_e32 v[30:31], 0
	v_mov_b64_e32 v[32:33], 0
	v_mov_b64_e32 v[2:3], 0
	v_mov_b64_e32 v[4:5], 0
	v_mov_b64_e32 v[6:7], 0
	v_mov_b64_e32 v[8:9], 0
	v_mov_b64_e32 v[10:11], 0
	v_mov_b64_e32 v[12:13], 0
	v_mov_b64_e32 v[14:15], 0
	v_mov_b64_e32 v[16:17], 0
	s_waitcnt vmcnt(0)
	s_barrier
	ds_read_b128 v[196:199], v194 offset:0
	ds_read_b128 v[212:215], v160 offset:0
	ds_read_b128 v[216:219], v160 offset:2048
	ds_read_b128 v[242:245], v160 offset:4096
	ds_read_b128 v[246:249], v160 offset:6144
	ds_read_b128 v[200:203], v194 offset:4096
	ds_read_b128 v[204:207], v194 offset:8192
	ds_read_b128 v[208:211], v194 offset:12288
; #define MFMA32(a, b, c) __builtin_amdgcn_mfma_f32_32x32x16_bf16((a), (b), (c), 0, 0, 0)
; DI void gemm256(const char* a_u, unsigned a_voff, size_t astep, const char* b_u, unsigned b_voff, size_t bstep, int nk, char* smem, f32x16 (&acc)[4][2]) {
;     ...
;   for (int kt = 0; kt < nk; ++kt) {
;     const int cur = kt & 1, k2 = (kt + 2 < last) ? kt + 2 : last;
;     const char* S = smem + cur * 2 * T2;
;     char* D = smem + (cur ^ 1) * 2 * T2;
;     const char* an = a_u + (size_t)k2 * 128;
;     const char* bn = b_u + (size_t)k2 * 128;
; #pragma unroll
;     for (int s = 0; s < 4; ++s) {
;       bf16x8 a[4], b[2];
; #pragma unroll
;       for (int mi = 0; mi < 4; ++mi) a[mi] = *(const bf16x8*)(S + aoff + mi * 32 * LROW + s * 32);
; #pragma unroll
;       for (int ni = 0; ni < 2; ++ni) b[ni] = *(const bf16x8*)(S + boff + ni * 32 * LROW + s * 32);
;       *(u32x4*)(D + soff + s * 64 * LROW) = ra[s];
;       *(u32x4*)(D + T2 + soff + s * 64 * LROW) = rb[s];
;       ra[s] = *(const u32x4*)(an + s * astep + a_voff);
;       rb[s] = *(const u32x4*)(bn + s * bstep + b_voff);
; #pragma unroll
;       for (int mi = 0; mi < 4; ++mi)
; #pragma unroll
;         for (int ni = 0; ni < 2; ++ni) acc[mi][ni] = MFMA32(a[mi], b[ni], acc[mi][ni]);
;     }
;     __syncthreads();
;   }
.Lg_down_loop:
	s_add_i32 s56, s56, 1
	s_add_u32 m0, s58, 0x8000
	s_nop 0
	global_load_lds_dwordx4 v164, s[52:53]
	s_add_u32 m0, s58, 0x8400
	s_nop 0
	global_load_lds_dwordx4 v165, s[52:53]
	s_add_u32 m0, s58, 0x8800
	s_nop 0
	global_load_lds_dwordx4 v130, s[52:53]
	s_add_u32 m0, s58, 0x8c00
	s_nop 0
	global_load_lds_dwordx4 v131, s[52:53]
	s_add_u32 m0, s59, 0x8000
	s_nop 0
	global_load_lds_dwordx4 v164, s[54:55]
	s_add_u32 m0, s59, 0x8400
	s_nop 0
	global_load_lds_dwordx4 v165, s[54:55]
	s_add_u32 m0, s59, 0x8800
	s_nop 0
	global_load_lds_dwordx4 v130, s[54:55]
	s_add_u32 m0, s59, 0x8c00
	s_nop 0
	global_load_lds_dwordx4 v131, s[54:55]
	s_waitcnt lgkmcnt(0)
	v_mfma_f32_16x16x32_bf16 v[114:117], v[196:199], v[212:215], v[114:117]
	ds_read_b128 v[220:223], v194 offset:2048
	v_mfma_f32_16x16x32_bf16 v[118:121], v[196:199], v[216:219], v[118:121]
	ds_read_b128 v[224:227], v194 offset:6144
	v_mfma_f32_16x16x32_bf16 v[98:101], v[196:199], v[242:245], v[98:101]
	ds_read_b128 v[228:231], v194 offset:10240
	v_mfma_f32_16x16x32_bf16 v[102:105], v[196:199], v[246:249], v[102:105]
	ds_read_b128 v[238:241], v194 offset:14336
	v_mfma_f32_16x16x32_bf16 v[82:85], v[200:203], v[212:215], v[82:85]
	v_mfma_f32_16x16x32_bf16 v[86:89], v[200:203], v[216:219], v[86:89]
	v_mfma_f32_16x16x32_bf16 v[66:69], v[200:203], v[242:245], v[66:69]
	v_mfma_f32_16x16x32_bf16 v[70:73], v[200:203], v[246:249], v[70:73]
	v_mfma_f32_16x16x32_bf16 v[50:53], v[204:207], v[212:215], v[50:53]
	v_mfma_f32_16x16x32_bf16 v[54:57], v[204:207], v[216:219], v[54:57]
	v_mfma_f32_16x16x32_bf16 v[34:37], v[204:207], v[242:245], v[34:37]
	v_mfma_f32_16x16x32_bf16 v[38:41], v[204:207], v[246:249], v[38:41]
	v_mfma_f32_16x16x32_bf16 v[18:21], v[208:211], v[212:215], v[18:21]
	v_mfma_f32_16x16x32_bf16 v[22:25], v[208:211], v[216:219], v[22:25]
	v_mfma_f32_16x16x32_bf16 v[2:5], v[208:211], v[242:245], v[2:5]
	v_mfma_f32_16x16x32_bf16 v[6:9], v[208:211], v[246:249], v[6:9]
	s_waitcnt lgkmcnt(0)
	v_mfma_f32_16x16x32_bf16 v[122:125], v[220:223], v[212:215], v[122:125]
	ds_read_b128 v[196:199], v195 offset:0
	v_mfma_f32_16x16x32_bf16 v[126:129], v[220:223], v[216:219], v[126:129]
	ds_read_b128 v[140:143], v161 offset:0
	v_mfma_f32_16x16x32_bf16 v[106:109], v[220:223], v[242:245], v[106:109]
	ds_read_b128 v[144:147], v161 offset:2048
	v_mfma_f32_16x16x32_bf16 v[110:113], v[220:223], v[246:249], v[110:113]
	ds_read_b128 v[148:151], v161 offset:4096
	v_mfma_f32_16x16x32_bf16 v[90:93], v[224:227], v[212:215], v[90:93]
	ds_read_b128 v[152:155], v161 offset:6144
	v_mfma_f32_16x16x32_bf16 v[94:97], v[224:227], v[216:219], v[94:97]
	ds_read_b128 v[200:203], v195 offset:4096
	v_mfma_f32_16x16x32_bf16 v[74:77], v[224:227], v[242:245], v[74:77]
	ds_read_b128 v[204:207], v195 offset:8192
	v_mfma_f32_16x16x32_bf16 v[78:81], v[224:227], v[246:249], v[78:81]
	ds_read_b128 v[208:211], v195 offset:12288
	v_mfma_f32_16x16x32_bf16 v[58:61], v[228:231], v[212:215], v[58:61]
	v_mfma_f32_16x16x32_bf16 v[62:65], v[228:231], v[216:219], v[62:65]
	v_mfma_f32_16x16x32_bf16 v[42:45], v[228:231], v[242:245], v[42:45]
	v_mfma_f32_16x16x32_bf16 v[46:49], v[228:231], v[246:249], v[46:49]
	v_mfma_f32_16x16x32_bf16 v[26:29], v[238:241], v[212:215], v[26:29]
	v_mfma_f32_16x16x32_bf16 v[30:33], v[238:241], v[216:219], v[30:33]
	v_mfma_f32_16x16x32_bf16 v[10:13], v[238:241], v[242:245], v[10:13]
	v_mfma_f32_16x16x32_bf16 v[14:17], v[238:241], v[246:249], v[14:17]
	s_waitcnt lgkmcnt(0)
	v_mfma_f32_16x16x32_bf16 v[114:117], v[196:199], v[140:143], v[114:117]
	ds_read_b128 v[220:223], v195 offset:2048
	v_mfma_f32_16x16x32_bf16 v[118:121], v[196:199], v[144:147], v[118:121]
	ds_read_b128 v[224:227], v195 offset:6144
	v_mfma_f32_16x16x32_bf16 v[98:101], v[196:199], v[148:151], v[98:101]
	ds_read_b128 v[228:231], v195 offset:10240
	v_mfma_f32_16x16x32_bf16 v[102:105], v[196:199], v[152:155], v[102:105]
	ds_read_b128 v[238:241], v195 offset:14336
	v_mfma_f32_16x16x32_bf16 v[82:85], v[200:203], v[140:143], v[82:85]
	v_mfma_f32_16x16x32_bf16 v[86:89], v[200:203], v[144:147], v[86:89]
	v_mfma_f32_16x16x32_bf16 v[66:69], v[200:203], v[148:151], v[66:69]
	v_mfma_f32_16x16x32_bf16 v[70:73], v[200:203], v[152:155], v[70:73]
	v_mfma_f32_16x16x32_bf16 v[50:53], v[204:207], v[140:143], v[50:53]
	v_mfma_f32_16x16x32_bf16 v[54:57], v[204:207], v[144:147], v[54:57]
	s_cmp_lt_u32 s56, s57
	s_cselect_b32 s60, 0x80, 0
	s_add_u32 s52, s52, s60
	s_addc_u32 s53, s53, 0
	s_add_u32 s54, s54, s60
	s_addc_u32 s55, s55, 0
	v_mfma_f32_16x16x32_bf16 v[34:37], v[204:207], v[148:151], v[34:37]
	v_mfma_f32_16x16x32_bf16 v[38:41], v[204:207], v[152:155], v[38:41]
	v_mfma_f32_16x16x32_bf16 v[18:21], v[208:211], v[140:143], v[18:21]
	v_mfma_f32_16x16x32_bf16 v[22:25], v[208:211], v[144:147], v[22:25]
	v_mfma_f32_16x16x32_bf16 v[2:5], v[208:211], v[148:151], v[2:5]
	v_mfma_f32_16x16x32_bf16 v[6:9], v[208:211], v[152:155], v[6:9]
	s_waitcnt lgkmcnt(0)
	v_mfma_f32_16x16x32_bf16 v[122:125], v[220:223], v[140:143], v[122:125]
	v_mfma_f32_16x16x32_bf16 v[126:129], v[220:223], v[144:147], v[126:129]
	v_mfma_f32_16x16x32_bf16 v[106:109], v[220:223], v[148:151], v[106:109]
	v_mfma_f32_16x16x32_bf16 v[110:113], v[220:223], v[152:155], v[110:113]
	v_mfma_f32_16x16x32_bf16 v[90:93], v[224:227], v[140:143], v[90:93]
	v_mfma_f32_16x16x32_bf16 v[94:97], v[224:227], v[144:147], v[94:97]
	v_mfma_f32_16x16x32_bf16 v[74:77], v[224:227], v[148:151], v[74:77]
	v_mfma_f32_16x16x32_bf16 v[78:81], v[224:227], v[152:155], v[78:81]
	v_mfma_f32_16x16x32_bf16 v[58:61], v[228:231], v[140:143], v[58:61]
	v_mfma_f32_16x16x32_bf16 v[62:65], v[228:231], v[144:147], v[62:65]
	v_mfma_f32_16x16x32_bf16 v[42:45], v[228:231], v[148:151], v[42:45]
	v_mfma_f32_16x16x32_bf16 v[46:49], v[228:231], v[152:155], v[46:49]
	v_mfma_f32_16x16x32_bf16 v[26:29], v[238:241], v[140:143], v[26:29]
	v_mfma_f32_16x16x32_bf16 v[30:33], v[238:241], v[144:147], v[30:33]
	v_mfma_f32_16x16x32_bf16 v[10:13], v[238:241], v[148:151], v[10:13]
	v_mfma_f32_16x16x32_bf16 v[14:17], v[238:241], v[152:155], v[14:17]
	s_waitcnt vmcnt(0)
	s_barrier
; #define MFMA32(a, b, c) __builtin_amdgcn_mfma_f32_32x32x16_bf16((a), (b), (c), 0, 0, 0)
; DI void gemm256(const char* a_u, unsigned a_voff, size_t astep, const char* b_u, unsigned b_voff, size_t bstep, int nk, char* smem, f32x16 (&acc)[4][2]) {
;     ...
;   for (int kt = 0; kt < nk; ++kt) {
;     const int cur = kt & 1, k2 = (kt + 2 < last) ? kt + 2 : last;
;     const char* S = smem + cur * 2 * T2;
;     char* D = smem + (cur ^ 1) * 2 * T2;
;     const char* an = a_u + (size_t)k2 * 128;
;     const char* bn = b_u + (size_t)k2 * 128;
; #pragma unroll
;     for (int s = 0; s < 4; ++s) {
;       bf16x8 a[4], b[2];
; #pragma unroll
;       for (int mi = 0; mi < 4; ++mi) a[mi] = *(const bf16x8*)(S + aoff + mi * 32 * LROW + s * 32);
; #pragma unroll
;       for (int ni = 0; ni < 2; ++ni) b[ni] = *(const bf16x8*)(S + boff + ni * 32 * LROW + s * 32);
;       *(u32x4*)(D + soff + s * 64 * LROW) = ra[s];
;       *(u32x4*)(D + T2 + soff + s * 64 * LROW) = rb[s];
;       ra[s] = *(const u32x4*)(an + s * astep + a_voff);
;       rb[s] = *(const u32x4*)(bn + s * bstep + b_voff);
; #pragma unroll
;       for (int mi = 0; mi < 4; ++mi)
; #pragma unroll
;         for (int ni = 0; ni < 2; ++ni) acc[mi][ni] = MFMA32(a[mi], b[ni], acc[mi][ni]);
;     }
;     __syncthreads();
;   }
	ds_read_b128 v[196:199], v194 offset:32768
	ds_read_b128 v[212:215], v160 offset:32768
	ds_read_b128 v[216:219], v160 offset:34816
	ds_read_b128 v[242:245], v160 offset:36864
	ds_read_b128 v[246:249], v160 offset:38912
	ds_read_b128 v[200:203], v194 offset:36864
	ds_read_b128 v[204:207], v194 offset:40960
	ds_read_b128 v[208:211], v194 offset:45056
	s_add_i32 s56, s56, 1
	s_add_u32 m0, s58, 0x0
	s_nop 0
	global_load_lds_dwordx4 v164, s[52:53]
	s_add_u32 m0, s58, 0x400
	s_nop 0
	global_load_lds_dwordx4 v165, s[52:53]
	s_add_u32 m0, s58, 0x800
	s_nop 0
	global_load_lds_dwordx4 v130, s[52:53]
	s_add_u32 m0, s58, 0xc00
	s_nop 0
	global_load_lds_dwordx4 v131, s[52:53]
	s_add_u32 m0, s59, 0x0
	s_nop 0
	global_load_lds_dwordx4 v164, s[54:55]
	s_add_u32 m0, s59, 0x400
	s_nop 0
	global_load_lds_dwordx4 v165, s[54:55]
	s_add_u32 m0, s59, 0x800
	s_nop 0
	global_load_lds_dwordx4 v130, s[54:55]
	s_add_u32 m0, s59, 0xc00
	s_nop 0
	global_load_lds_dwordx4 v131, s[54:55]
	s_waitcnt lgkmcnt(0)
	v_mfma_f32_16x16x32_bf16 v[114:117], v[196:199], v[212:215], v[114:117]
	ds_read_b128 v[220:223], v194 offset:34816
	v_mfma_f32_16x16x32_bf16 v[118:121], v[196:199], v[216:219], v[118:121]
	ds_read_b128 v[224:227], v194 offset:38912
	v_mfma_f32_16x16x32_bf16 v[98:101], v[196:199], v[242:245], v[98:101]
	ds_read_b128 v[228:231], v194 offset:43008
	v_mfma_f32_16x16x32_bf16 v[102:105], v[196:199], v[246:249], v[102:105]
	ds_read_b128 v[238:241], v194 offset:47104
	v_mfma_f32_16x16x32_bf16 v[82:85], v[200:203], v[212:215], v[82:85]
	v_mfma_f32_16x16x32_bf16 v[86:89], v[200:203], v[216:219], v[86:89]
	v_mfma_f32_16x16x32_bf16 v[66:69], v[200:203], v[242:245], v[66:69]
	v_mfma_f32_16x16x32_bf16 v[70:73], v[200:203], v[246:249], v[70:73]
	v_mfma_f32_16x16x32_bf16 v[50:53], v[204:207], v[212:215], v[50:53]
	v_mfma_f32_16x16x32_bf16 v[54:57], v[204:207], v[216:219], v[54:57]
	v_mfma_f32_16x16x32_bf16 v[34:37], v[204:207], v[242:245], v[34:37]
	v_mfma_f32_16x16x32_bf16 v[38:41], v[204:207], v[246:249], v[38:41]
	v_mfma_f32_16x16x32_bf16 v[18:21], v[208:211], v[212:215], v[18:21]
	v_mfma_f32_16x16x32_bf16 v[22:25], v[208:211], v[216:219], v[22:25]
	v_mfma_f32_16x16x32_bf16 v[2:5], v[208:211], v[242:245], v[2:5]
	v_mfma_f32_16x16x32_bf16 v[6:9], v[208:211], v[246:249], v[6:9]
	s_waitcnt lgkmcnt(0)
	v_mfma_f32_16x16x32_bf16 v[122:125], v[220:223], v[212:215], v[122:125]
	ds_read_b128 v[196:199], v195 offset:32768
	v_mfma_f32_16x16x32_bf16 v[126:129], v[220:223], v[216:219], v[126:129]
	ds_read_b128 v[140:143], v161 offset:32768
	v_mfma_f32_16x16x32_bf16 v[106:109], v[220:223], v[242:245], v[106:109]
	ds_read_b128 v[144:147], v161 offset:34816
	v_mfma_f32_16x16x32_bf16 v[110:113], v[220:223], v[246:249], v[110:113]
	ds_read_b128 v[148:151], v161 offset:36864
	v_mfma_f32_16x16x32_bf16 v[90:93], v[224:227], v[212:215], v[90:93]
	ds_read_b128 v[152:155], v161 offset:38912
	v_mfma_f32_16x16x32_bf16 v[94:97], v[224:227], v[216:219], v[94:97]
	ds_read_b128 v[200:203], v195 offset:36864
	v_mfma_f32_16x16x32_bf16 v[74:77], v[224:227], v[242:245], v[74:77]
	ds_read_b128 v[204:207], v195 offset:40960
	v_mfma_f32_16x16x32_bf16 v[78:81], v[224:227], v[246:249], v[78:81]
	ds_read_b128 v[208:211], v195 offset:45056
	v_mfma_f32_16x16x32_bf16 v[58:61], v[228:231], v[212:215], v[58:61]
	v_mfma_f32_16x16x32_bf16 v[62:65], v[228:231], v[216:219], v[62:65]
	v_mfma_f32_16x16x32_bf16 v[42:45], v[228:231], v[242:245], v[42:45]
	v_mfma_f32_16x16x32_bf16 v[46:49], v[228:231], v[246:249], v[46:49]
	v_mfma_f32_16x16x32_bf16 v[26:29], v[238:241], v[212:215], v[26:29]
	v_mfma_f32_16x16x32_bf16 v[30:33], v[238:241], v[216:219], v[30:33]
	v_mfma_f32_16x16x32_bf16 v[10:13], v[238:241], v[242:245], v[10:13]
	v_mfma_f32_16x16x32_bf16 v[14:17], v[238:241], v[246:249], v[14:17]
	s_waitcnt lgkmcnt(0)
	v_mfma_f32_16x16x32_bf16 v[114:117], v[196:199], v[140:143], v[114:117]
	ds_read_b128 v[220:223], v195 offset:34816
	v_mfma_f32_16x16x32_bf16 v[118:121], v[196:199], v[144:147], v[118:121]
	ds_read_b128 v[224:227], v195 offset:38912
	v_mfma_f32_16x16x32_bf16 v[98:101], v[196:199], v[148:151], v[98:101]
	ds_read_b128 v[228:231], v195 offset:43008
	v_mfma_f32_16x16x32_bf16 v[102:105], v[196:199], v[152:155], v[102:105]
	ds_read_b128 v[238:241], v195 offset:47104
	v_mfma_f32_16x16x32_bf16 v[82:85], v[200:203], v[140:143], v[82:85]
	v_mfma_f32_16x16x32_bf16 v[86:89], v[200:203], v[144:147], v[86:89]
	v_mfma_f32_16x16x32_bf16 v[66:69], v[200:203], v[148:151], v[66:69]
	v_mfma_f32_16x16x32_bf16 v[70:73], v[200:203], v[152:155], v[70:73]
	v_mfma_f32_16x16x32_bf16 v[50:53], v[204:207], v[140:143], v[50:53]
	v_mfma_f32_16x16x32_bf16 v[54:57], v[204:207], v[144:147], v[54:57]
	s_cmp_lt_u32 s56, s57
	s_cselect_b32 s60, 0x80, 0
	s_add_u32 s52, s52, s60
	s_addc_u32 s53, s53, 0
	s_add_u32 s54, s54, s60
	s_addc_u32 s55, s55, 0
	v_mfma_f32_16x16x32_bf16 v[34:37], v[204:207], v[148:151], v[34:37]
	v_mfma_f32_16x16x32_bf16 v[38:41], v[204:207], v[152:155], v[38:41]
	v_mfma_f32_16x16x32_bf16 v[18:21], v[208:211], v[140:143], v[18:21]
	v_mfma_f32_16x16x32_bf16 v[22:25], v[208:211], v[144:147], v[22:25]
	v_mfma_f32_16x16x32_bf16 v[2:5], v[208:211], v[148:151], v[2:5]
	v_mfma_f32_16x16x32_bf16 v[6:9], v[208:211], v[152:155], v[6:9]
	s_waitcnt lgkmcnt(0)
	v_mfma_f32_16x16x32_bf16 v[122:125], v[220:223], v[140:143], v[122:125]
	v_mfma_f32_16x16x32_bf16 v[126:129], v[220:223], v[144:147], v[126:129]
	v_mfma_f32_16x16x32_bf16 v[106:109], v[220:223], v[148:151], v[106:109]
	v_mfma_f32_16x16x32_bf16 v[110:113], v[220:223], v[152:155], v[110:113]
	v_mfma_f32_16x16x32_bf16 v[90:93], v[224:227], v[140:143], v[90:93]
	v_mfma_f32_16x16x32_bf16 v[94:97], v[224:227], v[144:147], v[94:97]
	v_mfma_f32_16x16x32_bf16 v[74:77], v[224:227], v[148:151], v[74:77]
	v_mfma_f32_16x16x32_bf16 v[78:81], v[224:227], v[152:155], v[78:81]
	v_mfma_f32_16x16x32_bf16 v[58:61], v[228:231], v[140:143], v[58:61]
	v_mfma_f32_16x16x32_bf16 v[62:65], v[228:231], v[144:147], v[62:65]
	v_mfma_f32_16x16x32_bf16 v[42:45], v[228:231], v[148:151], v[42:45]
	v_mfma_f32_16x16x32_bf16 v[46:49], v[228:231], v[152:155], v[46:49]
	v_mfma_f32_16x16x32_bf16 v[26:29], v[238:241], v[140:143], v[26:29]
	v_mfma_f32_16x16x32_bf16 v[30:33], v[238:241], v[144:147], v[30:33]
	v_mfma_f32_16x16x32_bf16 v[10:13], v[238:241], v[148:151], v[10:13]
	v_mfma_f32_16x16x32_bf16 v[14:17], v[238:241], v[152:155], v[14:17]
	s_waitcnt vmcnt(0)
	s_barrier
; #define MFMA32(a, b, c) __builtin_amdgcn_mfma_f32_32x32x16_bf16((a), (b), (c), 0, 0, 0)
; DI void gemm256(const char* a_u, unsigned a_voff, size_t astep, const char* b_u, unsigned b_voff, size_t bstep, int nk, char* smem, f32x16 (&acc)[4][2]) {
;     ...
;   for (int kt = 0; kt < nk; ++kt) {
;     const int cur = kt & 1, k2 = (kt + 2 < last) ? kt + 2 : last;
;     const char* S = smem + cur * 2 * T2;
;     char* D = smem + (cur ^ 1) * 2 * T2;
;     const char* an = a_u + (size_t)k2 * 128;
;     const char* bn = b_u + (size_t)k2 * 128;
; #pragma unroll
;     for (int s = 0; s < 4; ++s) {
;       bf16x8 a[4], b[2];
; #pragma unroll
;       for (int mi = 0; mi < 4; ++mi) a[mi] = *(const bf16x8*)(S + aoff + mi * 32 * LROW + s * 32);
; #pragma unroll
;       for (int ni = 0; ni < 2; ++ni) b[ni] = *(const bf16x8*)(S + boff + ni * 32 * LROW + s * 32);
;       *(u32x4*)(D + soff + s * 64 * LROW) = ra[s];
;       *(u32x4*)(D + T2 + soff + s * 64 * LROW) = rb[s];
;       ra[s] = *(const u32x4*)(an + s * astep + a_voff);
;       rb[s] = *(const u32x4*)(bn + s * bstep + b_voff);
; #pragma unroll
;       for (int mi = 0; mi < 4; ++mi)
; #pragma unroll
;         for (int ni = 0; ni < 2; ++ni) acc[mi][ni] = MFMA32(a[mi], b[ni], acc[mi][ni]);
;     }
;     __syncthreads();
;   }
	ds_read_b128 v[196:199], v194 offset:0
	ds_read_b128 v[212:215], v160 offset:0
	ds_read_b128 v[216:219], v160 offset:2048
	ds_read_b128 v[242:245], v160 offset:4096
	ds_read_b128 v[246:249], v160 offset:6144
	ds_read_b128 v[200:203], v194 offset:4096
	ds_read_b128 v[204:207], v194 offset:8192
	ds_read_b128 v[208:211], v194 offset:12288
	s_cmp_lt_u32 s56, s57
	s_cbranch_scc1 .Lg_down_loop
	s_waitcnt vmcnt(0) lgkmcnt(0)
	s_nop 7
	s_nop 7
	v_permlane16_swap_b32_e32 v114, v118
	v_permlane16_swap_b32_e32 v115, v119
	v_permlane16_swap_b32_e32 v116, v120
	v_permlane16_swap_b32_e32 v117, v121
	v_permlane16_swap_b32_e32 v122, v126
	v_permlane16_swap_b32_e32 v123, v127
	v_permlane16_swap_b32_e32 v124, v128
	v_permlane16_swap_b32_e32 v125, v129
	v_permlane16_swap_b32_e32 v98, v102
	v_permlane16_swap_b32_e32 v99, v103
	v_permlane16_swap_b32_e32 v100, v104
	v_permlane16_swap_b32_e32 v101, v105
	v_permlane16_swap_b32_e32 v106, v110
	v_permlane16_swap_b32_e32 v107, v111
	v_permlane16_swap_b32_e32 v108, v112
	v_permlane16_swap_b32_e32 v109, v113
	v_permlane16_swap_b32_e32 v82, v86
	v_permlane16_swap_b32_e32 v83, v87
	v_permlane16_swap_b32_e32 v84, v88
	v_permlane16_swap_b32_e32 v85, v89
	v_permlane16_swap_b32_e32 v90, v94
	v_permlane16_swap_b32_e32 v91, v95
	v_permlane16_swap_b32_e32 v92, v96
	v_permlane16_swap_b32_e32 v93, v97
	v_permlane16_swap_b32_e32 v66, v70
	v_permlane16_swap_b32_e32 v67, v71
	v_permlane16_swap_b32_e32 v68, v72
	v_permlane16_swap_b32_e32 v69, v73
	v_permlane16_swap_b32_e32 v74, v78
	v_permlane16_swap_b32_e32 v75, v79
	v_permlane16_swap_b32_e32 v76, v80
	v_permlane16_swap_b32_e32 v77, v81
	v_permlane16_swap_b32_e32 v50, v54
	v_permlane16_swap_b32_e32 v51, v55
	v_permlane16_swap_b32_e32 v52, v56
	v_permlane16_swap_b32_e32 v53, v57
	v_permlane16_swap_b32_e32 v58, v62
	v_permlane16_swap_b32_e32 v59, v63
	v_permlane16_swap_b32_e32 v60, v64
	v_permlane16_swap_b32_e32 v61, v65
	v_permlane16_swap_b32_e32 v34, v38
	v_permlane16_swap_b32_e32 v35, v39
	v_permlane16_swap_b32_e32 v36, v40
	v_permlane16_swap_b32_e32 v37, v41
	v_permlane16_swap_b32_e32 v42, v46
	v_permlane16_swap_b32_e32 v43, v47
	v_permlane16_swap_b32_e32 v44, v48
	v_permlane16_swap_b32_e32 v45, v49
	v_permlane16_swap_b32_e32 v18, v22
	v_permlane16_swap_b32_e32 v19, v23
	v_permlane16_swap_b32_e32 v20, v24
	v_permlane16_swap_b32_e32 v21, v25
	v_permlane16_swap_b32_e32 v26, v30
	v_permlane16_swap_b32_e32 v27, v31
	v_permlane16_swap_b32_e32 v28, v32
	v_permlane16_swap_b32_e32 v29, v33
	v_permlane16_swap_b32_e32 v2, v6
	v_permlane16_swap_b32_e32 v3, v7
	v_permlane16_swap_b32_e32 v4, v8
	v_permlane16_swap_b32_e32 v5, v9
	v_permlane16_swap_b32_e32 v10, v14
	v_permlane16_swap_b32_e32 v11, v15
	v_permlane16_swap_b32_e32 v12, v16
	v_permlane16_swap_b32_e32 v13, v17
	v_permlane32_swap_b32_e32 v114, v118
	v_permlane32_swap_b32_e32 v115, v119
	v_permlane32_swap_b32_e32 v116, v120
	v_permlane32_swap_b32_e32 v117, v121
	v_permlane32_swap_b32_e32 v122, v126
	v_permlane32_swap_b32_e32 v123, v127
	v_permlane32_swap_b32_e32 v124, v128
	v_permlane32_swap_b32_e32 v125, v129
	v_permlane32_swap_b32_e32 v98, v102
	v_permlane32_swap_b32_e32 v99, v103
	v_permlane32_swap_b32_e32 v100, v104
	v_permlane32_swap_b32_e32 v101, v105
	v_permlane32_swap_b32_e32 v106, v110
	v_permlane32_swap_b32_e32 v107, v111
	v_permlane32_swap_b32_e32 v108, v112
	v_permlane32_swap_b32_e32 v109, v113
	v_permlane32_swap_b32_e32 v82, v86
	v_permlane32_swap_b32_e32 v83, v87
	v_permlane32_swap_b32_e32 v84, v88
	v_permlane32_swap_b32_e32 v85, v89
	v_permlane32_swap_b32_e32 v90, v94
	v_permlane32_swap_b32_e32 v91, v95
	v_permlane32_swap_b32_e32 v92, v96
	v_permlane32_swap_b32_e32 v93, v97
	v_permlane32_swap_b32_e32 v66, v70
	v_permlane32_swap_b32_e32 v67, v71
	v_permlane32_swap_b32_e32 v68, v72
	v_permlane32_swap_b32_e32 v69, v73
	v_permlane32_swap_b32_e32 v74, v78
	v_permlane32_swap_b32_e32 v75, v79
	v_permlane32_swap_b32_e32 v76, v80
	v_permlane32_swap_b32_e32 v77, v81
	v_permlane32_swap_b32_e32 v50, v54
	v_permlane32_swap_b32_e32 v51, v55
	v_permlane32_swap_b32_e32 v52, v56
	v_permlane32_swap_b32_e32 v53, v57
	v_permlane32_swap_b32_e32 v58, v62
	v_permlane32_swap_b32_e32 v59, v63
	v_permlane32_swap_b32_e32 v60, v64
	v_permlane32_swap_b32_e32 v61, v65
	v_permlane32_swap_b32_e32 v34, v38
	v_permlane32_swap_b32_e32 v35, v39
	v_permlane32_swap_b32_e32 v36, v40
	v_permlane32_swap_b32_e32 v37, v41
	v_permlane32_swap_b32_e32 v42, v46
	v_permlane32_swap_b32_e32 v43, v47
	v_permlane32_swap_b32_e32 v44, v48
	v_permlane32_swap_b32_e32 v45, v49
	v_permlane32_swap_b32_e32 v18, v22
	v_permlane32_swap_b32_e32 v19, v23
	v_permlane32_swap_b32_e32 v20, v24
	v_permlane32_swap_b32_e32 v21, v25
	v_permlane32_swap_b32_e32 v26, v30
	v_permlane32_swap_b32_e32 v27, v31
	v_permlane32_swap_b32_e32 v28, v32
	v_permlane32_swap_b32_e32 v29, v33
	v_permlane32_swap_b32_e32 v2, v6
	v_permlane32_swap_b32_e32 v3, v7
	v_permlane32_swap_b32_e32 v4, v8
	v_permlane32_swap_b32_e32 v5, v9
	v_permlane32_swap_b32_e32 v10, v14
	v_permlane32_swap_b32_e32 v11, v15
	v_permlane32_swap_b32_e32 v12, v16
	v_permlane32_swap_b32_e32 v13, v17
	s_nop 1
	s_branch .LBB0_1646
